# attention: counted waits of a unit's first job count the previous unit's output stores while those are younger than the piece waited for
# speedup vs baseline: 1.0005x; 1.0005x over previous
.LBB0_296:
	v_writelane_b32 v244, s2, 31
	v_writelane_b32 v244, s84, 32
	v_writelane_b32 v244, s85, 33
	v_writelane_b32 v244, s86, 34
	v_writelane_b32 v244, s87, 35
	v_writelane_b32 v244, s96, 36
	v_writelane_b32 v244, s97, 37
	v_writelane_b32 v244, s50, 38
	v_writelane_b32 v244, s51, 39
	s_mov_b64 s[46:47], s[86:87]
	s_mov_b32 s10, s72
	v_readlane_b32 s11, v244, 0
	s_add_u32 s48, s46, 0x18800200
	s_addc_u32 s49, s47, 0
	s_add_u32 s50, s46, 0x1b00000
	s_addc_u32 s51, s47, 0
	s_mul_i32 s90, s10, 0x2800
	s_add_i32 s90, s90, 0x10800
	s_add_i32 s12, s90, 0x0
	s_add_i32 s13, s90, 0x800
	s_add_i32 s14, s90, 0x1000
	s_add_i32 s15, s90, 0x1800
	s_add_i32 s16, s90, 0x2000
	v_and_b32_e32 v146, 63, v214
	v_and_b32_e32 v216, 15, v146
	v_lshrrev_b32_e32 v217, 4, v146
	v_lshrrev_b32_e32 v218, 3, v146
	v_and_b32_e32 v219, 7, v146
	v_lshlrev_b32_e32 v229, 2, v217
	v_mov_b32_e32 v230, 0xff800000
	v_lshrrev_b32_e32 v147, 1, v218
	v_xor_b32_e32 v220, v219, v147
	v_xor_b32_e32 v221, 4, v220
	v_lshlrev_b32_e32 v220, 4, v220
	v_lshlrev_b32_e32 v221, 4, v221
	v_lshlrev_b32_e32 v148, 1, v147
	v_xor_b32_e32 v222, v219, v148
	v_lshlrev_b32_e32 v222, 4, v222
	v_lshrrev_b32_e32 v147, 1, v216
	v_xor_b32_e32 v148, v217, v147
	v_or_b32_e32 v149, 4, v217
	v_xor_b32_e32 v149, v149, v147
	v_lshlrev_b32_e32 v150, 7, v216
	v_lshl_add_u32 v223, v148, 4, v150
	v_lshl_add_u32 v224, v149, 4, v150
	v_lshrrev_b32_e32 v147, 2, v216
	v_lshl_add_u32 v147, v217, 2, v147
	v_and_b32_e32 v148, 3, v216
	v_lshrrev_b32_e32 v149, 1, v148
	v_bfe_u32 v150, v147, 1, 2
	v_lshlrev_b32_e32 v150, 1, v150
	v_and_b32_e32 v151, 1, v148
	v_lshlrev_b32_e32 v151, 3, v151
	v_lshl_add_u32 v151, v147, 7, v151
	v_or_b32_e32 v152, 0, v149
	v_xor_b32_e32 v152, v152, v150
	v_lshl_add_u32 v225, v152, 4, v151
	v_or_b32_e32 v152, 2, v149
	v_xor_b32_e32 v152, v152, v150
	v_lshl_add_u32 v226, v152, 4, v151
	v_or_b32_e32 v152, 4, v149
	v_xor_b32_e32 v152, v152, v150
	v_lshl_add_u32 v227, v152, 4, v151
	v_or_b32_e32 v152, 6, v149
	v_xor_b32_e32 v152, v152, v150
	v_lshl_add_u32 v228, v152, 4, v151
	v_and_b32_e32 v147, 1, v217
	v_lshrrev_b32_e32 v148, 1, v217
	v_lshlrev_b32_e32 v147, 5, v147
	v_lshl_add_u32 v233, v148, 4, v147
	v_or_b32_e32 v147, 0, v229
	v_cmp_lt_u32_e64 s[52:53], v147, v216
	v_cmp_gt_u32_e64 s[62:63], v147, v216
	v_or_b32_e32 v147, 1, v229
	v_cmp_lt_u32_e64 s[56:57], v147, v216
	v_cmp_gt_u32_e64 s[64:65], v147, v216
	v_or_b32_e32 v147, 2, v229
	v_cmp_lt_u32_e64 s[58:59], v147, v216
	v_cmp_gt_u32_e64 s[70:71], v147, v216
	v_or_b32_e32 v147, 3, v229
	v_cmp_lt_u32_e64 s[60:61], v147, v216
	v_cmp_gt_u32_e64 s[72:73], v147, v216
	v_cmp_eq_u32_e64 s[74:75], 0, v217
	s_lshl_b32 s82, s10, 5
	s_lshr_b32 s90, s10, 2
	s_and_b32 s91, s10, 3
	s_lshl_b32 s90, s90, 7
	s_add_i32 s83, s90, s91
	s_mov_b32 s84, s10
	s_add_i32 s85, s10, 8
	s_mul_hi_u32 s43, s11, 0xaaaaaaab
	s_lshr_b32 s43, s43, 7
	s_mul_i32 s90, s43, 0xc0
	s_sub_i32 s90, s11, s90
	s_lshl_b32 s42, s90, 8
	s_cmp_lt_u32 s90, 64
	s_mov_b32 s91, 0x7fffc000
	s_cselect_b32 s91, 0xfffff800, s91
	s_movk_i32 s40, 0x3fff
	s_cselect_b32 s40, 0x7ff, s40
	s_and_b32 s91, s91, s42
	s_sub_i32 s38, s42, s91
	s_mul_i32 s90, s43, 0x600000
	s_lshl_b32 s91, s91, 7
	s_add_u32 s90, s90, s91
	s_add_u32 s18, s46, 0x9800000
	s_addc_u32 s19, s47, 0
	s_add_u32 s18, s18, s90
	s_addc_u32 s19, s19, 0
	s_add_u32 s20, s46, 0xe000000
	s_addc_u32 s21, s47, 0
	s_add_u32 s20, s20, s90
	s_addc_u32 s21, s21, 0
	s_add_u32 s24, s46, 0x12800000
	s_addc_u32 s25, s47, 0
	s_add_u32 s24, s24, s90
	s_addc_u32 s25, s25, 0
	s_add_i32 s76, s38, s82
	v_lshlrev_b32_e32 v231, 0, v218
	v_add_u32_e32 v232, 8, v218
	v_lshlrev_b32_e32 v232, 0, v232
	s_add_i32 s93, s76, 0
	s_mov_b32 m0, s12
	v_add_u32_e32 v164, s93, v231
	v_lshl_or_b32 v164, v164, 7, v220
	global_load_lds_dwordx4 v164, s[18:19]
	s_add_i32 m0, s12, 0x400
	v_add_u32_e32 v165, s93, v232
	v_lshl_or_b32 v165, v165, 7, v221
	global_load_lds_dwordx4 v165, s[18:19]
	s_add_i32 s93, s76, 16
	s_mov_b32 m0, s13
	v_add_u32_e32 v164, s93, v231
	v_lshl_or_b32 v164, v164, 7, v220
	global_load_lds_dwordx4 v164, s[18:19]
	s_add_i32 m0, s13, 0x400
	v_add_u32_e32 v165, s93, v232
	v_lshl_or_b32 v165, v165, 7, v221
	global_load_lds_dwordx4 v165, s[18:19]
	s_add_i32 s93, s76, 0xffffffc0
	s_mov_b32 m0, s14
	v_add_u32_e32 v164, s93, v231
	v_med3_i32 v164, v164, 0, s40
	v_lshl_or_b32 v164, v164, 7, v220
	global_load_lds_dwordx4 v164, s[20:21]
	s_add_i32 m0, s14, 0x400
	v_add_u32_e32 v165, s93, v232
	v_med3_i32 v165, v165, 0, s40
	v_lshl_or_b32 v165, v165, 7, v221
	global_load_lds_dwordx4 v165, s[20:21]
	s_add_i32 s93, s76, 0xffffffd0
	s_mov_b32 m0, s15
	v_add_u32_e32 v164, s93, v231
	v_med3_i32 v164, v164, 0, s40
	v_lshl_or_b32 v164, v164, 7, v220
	global_load_lds_dwordx4 v164, s[20:21]
	s_add_i32 m0, s15, 0x400
	v_add_u32_e32 v165, s93, v232
	v_med3_i32 v165, v165, 0, s40
	v_lshl_or_b32 v165, v165, 7, v221
	global_load_lds_dwordx4 v165, s[20:21]
	s_add_i32 s93, s76, 0xffffffe0
	s_mov_b32 m0, s16
	v_add_u32_e32 v164, s93, v231
	v_med3_i32 v164, v164, 0, s40
	v_lshl_or_b32 v164, v164, 7, v220
	global_load_lds_dwordx4 v164, s[20:21]
	s_add_i32 m0, s16, 0x400
	v_add_u32_e32 v165, s93, v232
	v_med3_i32 v165, v165, 0, s40
	v_lshl_or_b32 v165, v165, 7, v221
	global_load_lds_dwordx4 v165, s[20:21]
	s_mov_b32 s9, 1
.Latt_unit:
	s_add_i32 s92, s11, s66
	s_cmpk_lt_u32 s92, 0x900
	s_cselect_b32 s92, s92, s11
	s_mul_hi_u32 s45, s92, 0xaaaaaaab
	s_lshr_b32 s45, s45, 7
	s_mul_i32 s90, s45, 0xc0
	s_sub_i32 s90, s92, s90
	s_lshl_b32 s44, s90, 8
	s_cmp_lt_u32 s90, 64
	s_mov_b32 s91, 0x7fffc000
	s_cselect_b32 s91, 0xfffff800, s91
	s_movk_i32 s41, 0x3fff
	s_cselect_b32 s41, 0x7ff, s41
	s_and_b32 s91, s91, s44
	s_sub_i32 s39, s44, s91
	s_mul_i32 s90, s45, 0x600000
	s_lshl_b32 s91, s91, 7
	s_add_u32 s90, s90, s91
	s_add_u32 s30, s46, 0x9800000
	s_addc_u32 s31, s47, 0
	s_add_u32 s30, s30, s90
	s_addc_u32 s31, s31, 0
	s_add_u32 s34, s46, 0xe000000
	s_addc_u32 s35, s47, 0
	s_add_u32 s34, s34, s90
	s_addc_u32 s35, s35, 0
	s_add_u32 s36, s46, 0x12800000
	s_addc_u32 s37, s47, 0
	s_add_u32 s36, s36, s90
	s_addc_u32 s37, s37, 0
	s_add_i32 s76, s38, s82
	s_add_i32 s79, s38, s83
	v_lshlrev_b32_e32 v231, 0, v218
	v_add_u32_e32 v232, 8, v218
	v_lshlrev_b32_e32 v232, 0, v232
	v_lshlrev_b32_e32 v162, 2, v218
	v_add_u32_e32 v163, 8, v218
	v_lshlrev_b32_e32 v163, 2, v163
	s_waitcnt vmcnt(14)
	s_cmp_eq_u32 s9, 1
	s_cbranch_scc0 .Latt_stw_1
	s_waitcnt vmcnt(8)
.Latt_stw_1:
	v_add_u32_e32 v154, s12, v223
	v_add_u32_e32 v155, s12, v224
	ds_read_b128 v[72:75], v154
	ds_read_b128 v[76:79], v155
	s_waitcnt lgkmcnt(0)
	s_add_i32 s93, s76, -16
	s_mov_b32 m0, s12
	v_add_u32_e32 v164, s93, v231
	v_med3_i32 v164, v164, 0, s40
	v_lshl_or_b32 v164, v164, 7, v220
	global_load_lds_dwordx4 v164, s[20:21]
	s_add_i32 m0, s12, 0x400
	v_add_u32_e32 v165, s93, v232
	v_med3_i32 v165, v165, 0, s40
	v_lshl_or_b32 v165, v165, 7, v221
	global_load_lds_dwordx4 v165, s[20:21]
	s_waitcnt vmcnt(14)
	s_cmp_eq_u32 s9, 1
	s_cbranch_scc0 .Latt_stw_2
	s_waitcnt vmcnt(8)
.Latt_stw_2:
	v_add_u32_e32 v154, s13, v223
	v_add_u32_e32 v155, s13, v224
	ds_read_b128 v[80:83], v154
	ds_read_b128 v[84:87], v155
	s_waitcnt lgkmcnt(0)
	s_add_i32 s93, s76, 0
	s_mov_b32 m0, s13
	v_add_u32_e32 v164, s93, v231
	v_med3_i32 v164, v164, 0, s40
	v_lshl_or_b32 v164, v164, 7, v220
	global_load_lds_dwordx4 v164, s[20:21]
	s_add_i32 m0, s13, 0x400
	v_add_u32_e32 v165, s93, v232
	v_med3_i32 v165, v165, 0, s40
	v_lshl_or_b32 v165, v165, 7, v221
	global_load_lds_dwordx4 v165, s[20:21]
	s_waitcnt vmcnt(14)
	s_cmp_eq_u32 s9, 1
	s_cbranch_scc0 .Latt_stw_3
	s_waitcnt vmcnt(8)
.Latt_stw_3:
	v_add_u32_e32 v154, s14, v223
	v_add_u32_e32 v155, s14, v224
	ds_read_b128 v[88:91], v154
	ds_read_b128 v[92:95], v155
	s_waitcnt lgkmcnt(0)
	s_add_i32 s93, s76, 16
	s_mov_b32 m0, s14
	v_add_u32_e32 v164, s93, v231
	v_med3_i32 v164, v164, 0, s40
	v_lshl_or_b32 v164, v164, 7, v220
	global_load_lds_dwordx4 v164, s[20:21]
	s_add_i32 m0, s14, 0x400
	v_add_u32_e32 v165, s93, v232
	v_med3_i32 v165, v165, 0, s40
	v_lshl_or_b32 v165, v165, 7, v221
	global_load_lds_dwordx4 v165, s[20:21]
	s_waitcnt vmcnt(14)
	s_cmp_eq_u32 s9, 1
	s_cbranch_scc0 .Latt_stw_4
	s_waitcnt vmcnt(8)
.Latt_stw_4:
	v_add_u32_e32 v154, s15, v223
	v_add_u32_e32 v155, s15, v224
	ds_read_b128 v[202:205], v154
	ds_read_b128 v[206:209], v155
	v_mfma_f32_16x16x32_bf16 v[0:3], v[88:91], v[72:75], 0
	v_mfma_f32_16x16x32_bf16 v[0:3], v[92:95], v[76:79], v[0:3]
	s_waitcnt lgkmcnt(0)
	s_add_i32 s93, s76, 32
	s_mov_b32 m0, s15
	v_add_u32_e32 v164, s93, v231
	v_med3_i32 v164, v164, 0, s40
	v_lshl_or_b32 v164, v164, 7, v220
	global_load_lds_dwordx4 v164, s[20:21]
	s_add_i32 m0, s15, 0x400
	v_add_u32_e32 v165, s93, v232
	v_med3_i32 v165, v165, 0, s40
	v_lshl_or_b32 v165, v165, 7, v221
	global_load_lds_dwordx4 v165, s[20:21]
	s_waitcnt vmcnt(14)
	s_cmp_eq_u32 s9, 1
	s_cbranch_scc0 .Latt_stw_5
	s_waitcnt vmcnt(8)
.Latt_stw_5:
	v_add_u32_e32 v154, s16, v223
	v_add_u32_e32 v155, s16, v224
	ds_read_b128 v[88:91], v154
	ds_read_b128 v[92:95], v155
	v_mfma_f32_16x16x32_bf16 v[4:7], v[202:205], v[72:75], 0
	v_mfma_f32_16x16x32_bf16 v[36:39], v[202:205], v[80:83], 0
	v_mfma_f32_16x16x32_bf16 v[4:7], v[206:209], v[76:79], v[4:7]
	v_mfma_f32_16x16x32_bf16 v[36:39], v[206:209], v[84:87], v[36:39]
	s_waitcnt lgkmcnt(0)
	s_add_i32 s93, s76, 48
	s_mov_b32 m0, s16
	v_add_u32_e32 v164, s93, v231
	v_med3_i32 v164, v164, 0, s40
	v_lshl_or_b32 v164, v164, 7, v220
	global_load_lds_dwordx4 v164, s[20:21]
	s_add_i32 m0, s16, 0x400
	v_add_u32_e32 v165, s93, v232
	v_med3_i32 v165, v165, 0, s40
	v_lshl_or_b32 v165, v165, 7, v221
	global_load_lds_dwordx4 v165, s[20:21]
	s_waitcnt vmcnt(8)
	v_add_u32_e32 v154, s12, v223
	v_add_u32_e32 v155, s12, v224
	ds_read_b128 v[202:205], v154
	ds_read_b128 v[206:209], v155
	v_mfma_f32_16x16x32_bf16 v[8:11], v[88:91], v[72:75], 0
	v_mfma_f32_16x16x32_bf16 v[40:43], v[88:91], v[80:83], 0
	v_mfma_f32_16x16x32_bf16 v[8:11], v[92:95], v[76:79], v[8:11]
	v_mfma_f32_16x16x32_bf16 v[40:43], v[92:95], v[84:87], v[40:43]
	v_mov_b32_e32 v188, s82
	v_add_u32_e32 v188, v216, v188
	v_lshrrev_b32_e32 v146, 4, v188
	v_xor_b32_e32 v146, v146, v188
	v_and_b32_e32 v146, 15, v146
	v_lshlrev_b32_e32 v147, 8, v188
	s_waitcnt lgkmcnt(0)
	s_add_i32 s93, s76, 64
	s_mov_b32 m0, s12
	v_add_u32_e32 v164, s93, v231
	v_med3_i32 v164, v164, 0, s40
	v_lshl_or_b32 v164, v164, 7, v220
	global_load_lds_dwordx4 v164, s[20:21]
	s_add_i32 m0, s12, 0x400
	v_add_u32_e32 v165, s93, v232
	v_med3_i32 v165, v165, 0, s40
	v_lshl_or_b32 v165, v165, 7, v221
	global_load_lds_dwordx4 v165, s[20:21]
	s_waitcnt vmcnt(8)
	v_add_u32_e32 v154, s13, v223
	v_add_u32_e32 v155, s13, v224
	ds_read_b128 v[88:91], v154
	ds_read_b128 v[92:95], v155
	v_mfma_f32_16x16x32_bf16 v[12:15], v[202:205], v[72:75], 0
	v_mfma_f32_16x16x32_bf16 v[44:47], v[202:205], v[80:83], 0
	v_mfma_f32_16x16x32_bf16 v[12:15], v[206:209], v[76:79], v[12:15]
	v_mfma_f32_16x16x32_bf16 v[44:47], v[206:209], v[84:87], v[44:47]
	v_or_b32_e32 v148, 0, v217
	v_xor_b32_e32 v148, v148, v146
	v_lshl_add_u32 v190, v148, 4, v147
	v_or_b32_e32 v148, 4, v217
	v_xor_b32_e32 v148, v148, v146
	v_lshl_add_u32 v191, v148, 4, v147
	s_waitcnt lgkmcnt(0)
	s_add_i32 s93, s76, 0x50
	s_mov_b32 m0, s13
	v_add_u32_e32 v164, s93, v231
	v_med3_i32 v164, v164, 0, s40
	v_lshl_or_b32 v164, v164, 7, v220
	global_load_lds_dwordx4 v164, s[20:21]
	s_add_i32 m0, s13, 0x400
	v_add_u32_e32 v165, s93, v232
	v_med3_i32 v165, v165, 0, s40
	v_lshl_or_b32 v165, v165, 7, v221
	global_load_lds_dwordx4 v165, s[20:21]
	s_waitcnt vmcnt(8)
	v_add_u32_e32 v154, s14, v223
	v_add_u32_e32 v155, s14, v224
	ds_read_b128 v[202:205], v154
	ds_read_b128 v[206:209], v155
	v_mfma_f32_16x16x32_bf16 v[16:19], v[88:91], v[72:75], 0
	v_mfma_f32_16x16x32_bf16 v[48:51], v[88:91], v[80:83], 0
	v_mfma_f32_16x16x32_bf16 v[16:19], v[92:95], v[76:79], v[16:19]
	v_mfma_f32_16x16x32_bf16 v[48:51], v[92:95], v[84:87], v[48:51]
	v_or_b32_e32 v148, 8, v217
	v_xor_b32_e32 v148, v148, v146
	v_lshl_add_u32 v192, v148, 4, v147
	v_or_b32_e32 v148, 12, v217
	v_xor_b32_e32 v148, v148, v146
	v_lshl_add_u32 v193, v148, 4, v147
	s_waitcnt lgkmcnt(0)
	s_add_i32 s93, s76, 0xffffffc0
	s_mov_b32 m0, s14
	v_add_u32_e32 v164, s93, v231
	v_med3_i32 v164, v164, 0, s40
	v_lshl_or_b32 v164, v164, 7, v222
	global_load_lds_dwordx4 v164, s[24:25]
	s_add_i32 m0, s14, 0x400
	v_add_u32_e32 v165, s93, v232
	v_med3_i32 v165, v165, 0, s40
	v_lshl_or_b32 v165, v165, 7, v222
	global_load_lds_dwordx4 v165, s[24:25]
	s_waitcnt vmcnt(8)
	v_add_u32_e32 v154, s15, v223
	v_add_u32_e32 v155, s15, v224
	ds_read_b128 v[88:91], v154
	ds_read_b128 v[92:95], v155
	v_mfma_f32_16x16x32_bf16 v[20:23], v[202:205], v[72:75], 0
	v_mfma_f32_16x16x32_bf16 v[52:55], v[202:205], v[80:83], 0
	v_mfma_f32_16x16x32_bf16 v[20:23], v[206:209], v[76:79], v[20:23]
	v_mfma_f32_16x16x32_bf16 v[52:55], v[206:209], v[84:87], v[52:55]
	v_lshlrev_b32_e32 v194, 3, v188
	v_add_u32_e32 v194, 0x10000, v194
	v_mov_b32_e32 v189, s82
	v_add_u32_e32 v189, v216, v189
	v_add_u32_e32 v189, 16, v189
	v_lshrrev_b32_e32 v146, 4, v189
	s_waitcnt lgkmcnt(0)
	s_add_i32 s93, s76, 0xffffffd0
	s_mov_b32 m0, s15
	v_add_u32_e32 v164, s93, v231
	v_med3_i32 v164, v164, 0, s40
	v_lshl_or_b32 v164, v164, 7, v222
	global_load_lds_dwordx4 v164, s[24:25]
	s_add_i32 m0, s15, 0x400
	v_add_u32_e32 v165, s93, v232
	v_med3_i32 v165, v165, 0, s40
	v_lshl_or_b32 v165, v165, 7, v222
	global_load_lds_dwordx4 v165, s[24:25]
	s_waitcnt vmcnt(8)
	v_add_u32_e32 v154, s16, v223
	v_add_u32_e32 v155, s16, v224
	ds_read_b128 v[202:205], v154
	ds_read_b128 v[206:209], v155
	v_mfma_f32_16x16x32_bf16 v[24:27], v[88:91], v[72:75], 0
	v_mfma_f32_16x16x32_bf16 v[56:59], v[88:91], v[80:83], 0
	v_mfma_f32_16x16x32_bf16 v[24:27], v[92:95], v[76:79], v[24:27]
	v_mfma_f32_16x16x32_bf16 v[56:59], v[92:95], v[84:87], v[56:59]
	v_xor_b32_e32 v146, v146, v189
	v_and_b32_e32 v146, 15, v146
	v_lshlrev_b32_e32 v147, 8, v189
	v_or_b32_e32 v148, 0, v217
	v_xor_b32_e32 v148, v148, v146
	v_lshl_add_u32 v195, v148, 4, v147
	s_waitcnt lgkmcnt(0)
	s_add_i32 s93, s76, 0xffffffe0
	s_mov_b32 m0, s16
	v_add_u32_e32 v164, s93, v231
	v_med3_i32 v164, v164, 0, s40
	v_lshl_or_b32 v164, v164, 7, v222
	global_load_lds_dwordx4 v164, s[24:25]
	s_add_i32 m0, s16, 0x400
	v_add_u32_e32 v165, s93, v232
	v_med3_i32 v165, v165, 0, s40
	v_lshl_or_b32 v165, v165, 7, v222
	global_load_lds_dwordx4 v165, s[24:25]
	s_waitcnt vmcnt(8)
	v_add_u32_e32 v154, s12, v223
	v_add_u32_e32 v155, s12, v224
	ds_read_b128 v[88:91], v154
	ds_read_b128 v[92:95], v155
	v_mfma_f32_16x16x32_bf16 v[28:31], v[202:205], v[72:75], 0
	v_mfma_f32_16x16x32_bf16 v[60:63], v[202:205], v[80:83], 0
	v_mfma_f32_16x16x32_bf16 v[28:31], v[206:209], v[76:79], v[28:31]
	v_mfma_f32_16x16x32_bf16 v[60:63], v[206:209], v[84:87], v[60:63]
	v_or_b32_e32 v148, 4, v217
	v_xor_b32_e32 v148, v148, v146
	v_lshl_add_u32 v196, v148, 4, v147
	v_or_b32_e32 v148, 8, v217
	v_xor_b32_e32 v148, v148, v146
	v_lshl_add_u32 v197, v148, 4, v147
	s_waitcnt lgkmcnt(0)
	s_add_i32 s93, s76, -16
	s_mov_b32 m0, s12
	v_add_u32_e32 v164, s93, v231
	v_med3_i32 v164, v164, 0, s40
	v_lshl_or_b32 v164, v164, 7, v222
	global_load_lds_dwordx4 v164, s[24:25]
	s_add_i32 m0, s12, 0x400
	v_add_u32_e32 v165, s93, v232
	v_med3_i32 v165, v165, 0, s40
	v_lshl_or_b32 v165, v165, 7, v222
	global_load_lds_dwordx4 v165, s[24:25]
	s_waitcnt vmcnt(8)
	v_add_u32_e32 v154, s13, v223
	v_add_u32_e32 v155, s13, v224
	ds_read_b128 v[202:205], v154
	ds_read_b128 v[206:209], v155
	v_mfma_f32_16x16x32_bf16 v[32:35], v[88:91], v[72:75], 0
	v_mfma_f32_16x16x32_bf16 v[64:67], v[88:91], v[80:83], 0
	v_mfma_f32_16x16x32_bf16 v[32:35], v[92:95], v[76:79], v[32:35]
	v_mfma_f32_16x16x32_bf16 v[64:67], v[92:95], v[84:87], v[64:67]
	v_or_b32_e32 v148, 12, v217
	v_xor_b32_e32 v148, v148, v146
	v_lshl_add_u32 v198, v148, 4, v147
	v_lshlrev_b32_e32 v199, 3, v189
	v_add_u32_e32 v199, 0x10000, v199
	s_waitcnt lgkmcnt(0)
	s_add_i32 s93, s76, 0
	s_mov_b32 m0, s13
	v_add_u32_e32 v164, s93, v231
	v_med3_i32 v164, v164, 0, s40
	v_lshl_or_b32 v164, v164, 7, v222
	global_load_lds_dwordx4 v164, s[24:25]
	s_add_i32 m0, s13, 0x400
	v_add_u32_e32 v165, s93, v232
	v_med3_i32 v165, v165, 0, s40
	v_lshl_or_b32 v165, v165, 7, v222
	global_load_lds_dwordx4 v165, s[24:25]
	s_waitcnt vmcnt(8)
	v_add_u32_e32 v154, s14, v225
	v_add_u32_e32 v155, s14, v226
	v_add_u32_e32 v156, s14, v227
	v_add_u32_e32 v157, s14, v228
	ds_read_b64_tr_b16 v[88:89], v154
	ds_read_b64_tr_b16 v[90:91], v155
	ds_read_b64_tr_b16 v[92:93], v156
	ds_read_b64_tr_b16 v[94:95], v157
	v_mfma_f32_16x16x32_bf16 v[68:71], v[202:205], v[80:83], 0
	v_mfma_f32_16x16x32_bf16 v[68:71], v[206:209], v[84:87], v[68:71]
	s_add_i32 s90, s76, 0x5f
	s_cmp_gt_i32 s90, s40
	s_cselect_b32 s96, 1, 0
	s_cmp_lt_i32 s76, 64
	s_cselect_b32 s96, 1, s96
	s_ashr_i32 s77, s76, 0
	s_sub_i32 s77, 64, s77
	s_sub_i32 s78, s40, s76
	s_ashr_i32 s78, s78, 0
	s_add_i32 s78, s78, 64
	v_cndmask_b32_e64 v0, v0, v230, s[52:53]
	v_cndmask_b32_e64 v32, v32, v230, s[62:63]
	v_cndmask_b32_e64 v1, v1, v230, s[56:57]
	v_cndmask_b32_e64 v33, v33, v230, s[64:65]
	v_cndmask_b32_e64 v2, v2, v230, s[58:59]
	v_cndmask_b32_e64 v34, v34, v230, s[70:71]
	v_cndmask_b32_e64 v3, v3, v230, s[60:61]
	v_cndmask_b32_e64 v35, v35, v230, s[72:73]
	s_cmp_eq_u32 s96, 0
	s_cbranch_scc1 .Latt_noedge_6
	v_sub_u32_e32 v200, s77, v229
	s_sub_i32 s91, s78, s77
	v_sub_u32_e32 v150, 0, v200
	v_sub_u32_e32 v151, 1, v200
	v_sub_u32_e32 v152, 2, v200
	v_sub_u32_e32 v153, 3, v200
	v_cmp_lt_u32_e64 s[94:95], s91, v150
	v_cmp_lt_u32_e64 s[86:87], s91, v151
	v_cmp_lt_u32_e64 s[0:1], s91, v152
	v_cmp_lt_u32_e64 s[2:3], s91, v153
	v_cndmask_b32_e64 v0, v0, v230, s[94:95]
	v_cndmask_b32_e64 v1, v1, v230, s[86:87]
	v_cndmask_b32_e64 v2, v2, v230, s[0:1]
	v_cndmask_b32_e64 v3, v3, v230, s[2:3]
	v_sub_u32_e32 v150, 16, v200
	v_sub_u32_e32 v151, 17, v200
	v_sub_u32_e32 v152, 18, v200
	v_sub_u32_e32 v153, 19, v200
	v_cmp_lt_u32_e64 s[94:95], s91, v150
	v_cmp_lt_u32_e64 s[86:87], s91, v151
	v_cmp_lt_u32_e64 s[0:1], s91, v152
	v_cmp_lt_u32_e64 s[2:3], s91, v153
	v_cndmask_b32_e64 v4, v4, v230, s[94:95]
	v_cndmask_b32_e64 v5, v5, v230, s[86:87]
	v_cndmask_b32_e64 v6, v6, v230, s[0:1]
	v_cndmask_b32_e64 v7, v7, v230, s[2:3]
	v_sub_u32_e32 v150, 32, v200
	v_sub_u32_e32 v151, 33, v200
	v_sub_u32_e32 v152, 34, v200
	v_sub_u32_e32 v153, 35, v200
	v_cmp_lt_u32_e64 s[94:95], s91, v150
	v_cmp_lt_u32_e64 s[86:87], s91, v151
	v_cmp_lt_u32_e64 s[0:1], s91, v152
	v_cmp_lt_u32_e64 s[2:3], s91, v153
	v_cndmask_b32_e64 v8, v8, v230, s[94:95]
	v_cndmask_b32_e64 v9, v9, v230, s[86:87]
	v_cndmask_b32_e64 v10, v10, v230, s[0:1]
	v_cndmask_b32_e64 v11, v11, v230, s[2:3]
	v_sub_u32_e32 v150, 48, v200
	v_sub_u32_e32 v151, 49, v200
	v_sub_u32_e32 v152, 50, v200
	v_sub_u32_e32 v153, 51, v200
	v_cmp_lt_u32_e64 s[94:95], s91, v150
	v_cmp_lt_u32_e64 s[86:87], s91, v151
	v_cmp_lt_u32_e64 s[0:1], s91, v152
	v_cmp_lt_u32_e64 s[2:3], s91, v153
	v_cndmask_b32_e64 v12, v12, v230, s[94:95]
	v_cndmask_b32_e64 v13, v13, v230, s[86:87]
	v_cndmask_b32_e64 v14, v14, v230, s[0:1]
	v_cndmask_b32_e64 v15, v15, v230, s[2:3]
	v_sub_u32_e32 v150, 64, v200
	v_sub_u32_e32 v151, 0x41, v200
	v_sub_u32_e32 v152, 0x42, v200
	v_sub_u32_e32 v153, 0x43, v200
	v_cmp_lt_u32_e64 s[94:95], s91, v150
	v_cmp_lt_u32_e64 s[86:87], s91, v151
	v_cmp_lt_u32_e64 s[0:1], s91, v152
	v_cmp_lt_u32_e64 s[2:3], s91, v153
	v_cndmask_b32_e64 v16, v16, v230, s[94:95]
	v_cndmask_b32_e64 v17, v17, v230, s[86:87]
	v_cndmask_b32_e64 v18, v18, v230, s[0:1]
	v_cndmask_b32_e64 v19, v19, v230, s[2:3]
	v_sub_u32_e32 v150, 0x50, v200
	v_sub_u32_e32 v151, 0x51, v200
	v_sub_u32_e32 v152, 0x52, v200
	v_sub_u32_e32 v153, 0x53, v200
	v_cmp_lt_u32_e64 s[94:95], s91, v150
	v_cmp_lt_u32_e64 s[86:87], s91, v151
	v_cmp_lt_u32_e64 s[0:1], s91, v152
	v_cmp_lt_u32_e64 s[2:3], s91, v153
	v_cndmask_b32_e64 v20, v20, v230, s[94:95]
	v_cndmask_b32_e64 v21, v21, v230, s[86:87]
	v_cndmask_b32_e64 v22, v22, v230, s[0:1]
	v_cndmask_b32_e64 v23, v23, v230, s[2:3]
	v_sub_u32_e32 v150, 0x60, v200
	v_sub_u32_e32 v151, 0x61, v200
	v_sub_u32_e32 v152, 0x62, v200
	v_sub_u32_e32 v153, 0x63, v200
	v_cmp_lt_u32_e64 s[94:95], s91, v150
	v_cmp_lt_u32_e64 s[86:87], s91, v151
	v_cmp_lt_u32_e64 s[0:1], s91, v152
	v_cmp_lt_u32_e64 s[2:3], s91, v153
	v_cndmask_b32_e64 v24, v24, v230, s[94:95]
	v_cndmask_b32_e64 v25, v25, v230, s[86:87]
	v_cndmask_b32_e64 v26, v26, v230, s[0:1]
	v_cndmask_b32_e64 v27, v27, v230, s[2:3]
	v_sub_u32_e32 v150, 0x70, v200
	v_sub_u32_e32 v151, 0x71, v200
	v_sub_u32_e32 v152, 0x72, v200
	v_sub_u32_e32 v153, 0x73, v200
	v_cmp_lt_u32_e64 s[94:95], s91, v150
	v_cmp_lt_u32_e64 s[86:87], s91, v151
	v_cmp_lt_u32_e64 s[0:1], s91, v152
	v_cmp_lt_u32_e64 s[2:3], s91, v153
	v_cndmask_b32_e64 v28, v28, v230, s[94:95]
	v_cndmask_b32_e64 v29, v29, v230, s[86:87]
	v_cndmask_b32_e64 v30, v30, v230, s[0:1]
	v_cndmask_b32_e64 v31, v31, v230, s[2:3]
	v_sub_u32_e32 v150, 0x80, v200
	v_sub_u32_e32 v151, 0x81, v200
	v_sub_u32_e32 v152, 0x82, v200
	v_sub_u32_e32 v153, 0x83, v200
	v_cmp_lt_u32_e64 s[94:95], s91, v150
	v_cmp_lt_u32_e64 s[86:87], s91, v151
	v_cmp_lt_u32_e64 s[0:1], s91, v152
	v_cmp_lt_u32_e64 s[2:3], s91, v153
	v_cndmask_b32_e64 v32, v32, v230, s[94:95]
	v_cndmask_b32_e64 v33, v33, v230, s[86:87]
	v_cndmask_b32_e64 v34, v34, v230, s[0:1]
	v_cndmask_b32_e64 v35, v35, v230, s[2:3]

.Latt_noedge_9:
	s_nop 1
	v_max3_f32 v186, v36, v37, v38
	v_max3_f32 v186, v186, v39, v40
	v_max3_f32 v186, v186, v41, v42
	v_max3_f32 v186, v186, v43, v44
	v_max3_f32 v186, v186, v45, v46
	v_max3_f32 v186, v186, v47, v48
	v_max3_f32 v186, v186, v49, v50
	v_max3_f32 v186, v186, v51, v52
	v_max3_f32 v186, v186, v53, v54
	v_max3_f32 v186, v186, v55, v56
	v_max3_f32 v186, v186, v57, v58
	v_max3_f32 v186, v186, v59, v60
	v_max3_f32 v186, v186, v61, v62
	v_max3_f32 v186, v186, v63, v64
	v_max3_f32 v186, v186, v65, v66
	v_max3_f32 v186, v186, v67, v68
	v_max3_f32 v186, v186, v69, v70
	v_max_f32_e32 v186, v186, v71
	v_mov_b32_e32 v146, v186
	s_nop 1
	v_permlane16_swap_b32_e32 v186, v146
	v_max_f32_e32 v186, v186, v146
	v_mov_b32_e32 v146, v186
	s_nop 1
	v_permlane32_swap_b32_e32 v186, v146
	v_max_f32_e32 v186, v186, v146
	v_pk_add_f32 v[36:37], v[36:37], v[186:187] op_sel_hi:[1,0] neg_lo:[0,1] neg_hi:[0,1]
	v_pk_add_f32 v[38:39], v[38:39], v[186:187] op_sel_hi:[1,0] neg_lo:[0,1] neg_hi:[0,1]
	v_pk_add_f32 v[40:41], v[40:41], v[186:187] op_sel_hi:[1,0] neg_lo:[0,1] neg_hi:[0,1]
	v_pk_add_f32 v[42:43], v[42:43], v[186:187] op_sel_hi:[1,0] neg_lo:[0,1] neg_hi:[0,1]
	v_exp_f32_e32 v36, v36
	v_exp_f32_e32 v37, v37
	v_exp_f32_e32 v38, v38
	v_exp_f32_e32 v39, v39
	v_pk_add_f32 v[44:45], v[44:45], v[186:187] op_sel_hi:[1,0] neg_lo:[0,1] neg_hi:[0,1]
	v_pk_add_f32 v[46:47], v[46:47], v[186:187] op_sel_hi:[1,0] neg_lo:[0,1] neg_hi:[0,1]
	v_exp_f32_e32 v40, v40
	v_exp_f32_e32 v41, v41
	v_exp_f32_e32 v42, v42
	v_exp_f32_e32 v43, v43
	v_pk_add_f32 v[48:49], v[48:49], v[186:187] op_sel_hi:[1,0] neg_lo:[0,1] neg_hi:[0,1]
	v_pk_add_f32 v[50:51], v[50:51], v[186:187] op_sel_hi:[1,0] neg_lo:[0,1] neg_hi:[0,1]
	v_exp_f32_e32 v44, v44
	v_exp_f32_e32 v45, v45
	v_exp_f32_e32 v46, v46
	v_exp_f32_e32 v47, v47
	v_pk_add_f32 v[52:53], v[52:53], v[186:187] op_sel_hi:[1,0] neg_lo:[0,1] neg_hi:[0,1]
	v_pk_add_f32 v[54:55], v[54:55], v[186:187] op_sel_hi:[1,0] neg_lo:[0,1] neg_hi:[0,1]
	v_exp_f32_e32 v48, v48
	v_exp_f32_e32 v49, v49
	v_exp_f32_e32 v50, v50
	v_exp_f32_e32 v51, v51
	v_pk_add_f32 v[56:57], v[56:57], v[186:187] op_sel_hi:[1,0] neg_lo:[0,1] neg_hi:[0,1]
	v_pk_add_f32 v[58:59], v[58:59], v[186:187] op_sel_hi:[1,0] neg_lo:[0,1] neg_hi:[0,1]
	v_exp_f32_e32 v52, v52
	v_exp_f32_e32 v53, v53
	v_exp_f32_e32 v54, v54
	v_exp_f32_e32 v55, v55
	v_pk_add_f32 v[60:61], v[60:61], v[186:187] op_sel_hi:[1,0] neg_lo:[0,1] neg_hi:[0,1]
	v_pk_add_f32 v[62:63], v[62:63], v[186:187] op_sel_hi:[1,0] neg_lo:[0,1] neg_hi:[0,1]
	v_exp_f32_e32 v56, v56
	v_exp_f32_e32 v57, v57
	v_exp_f32_e32 v58, v58
	v_exp_f32_e32 v59, v59
	v_pk_add_f32 v[64:65], v[64:65], v[186:187] op_sel_hi:[1,0] neg_lo:[0,1] neg_hi:[0,1]
	v_pk_add_f32 v[66:67], v[66:67], v[186:187] op_sel_hi:[1,0] neg_lo:[0,1] neg_hi:[0,1]
	v_exp_f32_e32 v60, v60
	v_exp_f32_e32 v61, v61
	v_exp_f32_e32 v62, v62
	v_exp_f32_e32 v63, v63
	v_pk_add_f32 v[68:69], v[68:69], v[186:187] op_sel_hi:[1,0] neg_lo:[0,1] neg_hi:[0,1]
	v_pk_add_f32 v[70:71], v[70:71], v[186:187] op_sel_hi:[1,0] neg_lo:[0,1] neg_hi:[0,1]
	v_exp_f32_e32 v64, v64
	v_exp_f32_e32 v65, v65
	v_exp_f32_e32 v66, v66
	v_exp_f32_e32 v67, v67
	v_exp_f32_e32 v68, v68
	v_exp_f32_e32 v69, v69
	v_exp_f32_e32 v70, v70
	v_exp_f32_e32 v71, v71
	s_nop 0
	v_pk_add_f32 v[146:147], v[36:37], v[38:39]
	v_pk_add_f32 v[148:149], v[40:41], v[42:43]
	v_pk_add_f32 v[146:147], v[146:147], v[44:45]
	v_pk_add_f32 v[148:149], v[148:149], v[46:47]
	v_pk_add_f32 v[146:147], v[146:147], v[48:49]
	v_pk_add_f32 v[148:149], v[148:149], v[50:51]
	v_pk_add_f32 v[146:147], v[146:147], v[52:53]
	v_pk_add_f32 v[148:149], v[148:149], v[54:55]
	v_pk_add_f32 v[146:147], v[146:147], v[56:57]
	v_pk_add_f32 v[148:149], v[148:149], v[58:59]
	v_pk_add_f32 v[146:147], v[146:147], v[60:61]
	v_pk_add_f32 v[148:149], v[148:149], v[62:63]
	v_pk_add_f32 v[146:147], v[146:147], v[64:65]
	v_pk_add_f32 v[148:149], v[148:149], v[66:67]
	v_pk_add_f32 v[146:147], v[146:147], v[68:69]
	v_pk_add_f32 v[148:149], v[148:149], v[70:71]
	s_nop 0
	v_pk_add_f32 v[146:147], v[146:147], v[148:149]
	s_nop 0
	v_add_f32_e32 v187, v146, v147
	v_cvt_pk_bf16_f32 v36, v36, v37
	v_cvt_pk_bf16_f32 v37, v38, v39
	v_cvt_pk_bf16_f32 v40, v40, v41
	v_cvt_pk_bf16_f32 v41, v42, v43
	v_cvt_pk_bf16_f32 v44, v44, v45
	v_cvt_pk_bf16_f32 v45, v46, v47
	v_cvt_pk_bf16_f32 v48, v48, v49
	v_cvt_pk_bf16_f32 v49, v50, v51
	v_cvt_pk_bf16_f32 v52, v52, v53
	v_cvt_pk_bf16_f32 v53, v54, v55
	v_cvt_pk_bf16_f32 v56, v56, v57
	v_cvt_pk_bf16_f32 v57, v58, v59
	v_cvt_pk_bf16_f32 v60, v60, v61
	v_cvt_pk_bf16_f32 v61, v62, v63
	v_cvt_pk_bf16_f32 v64, v64, v65
	v_cvt_pk_bf16_f32 v65, v66, v67
	v_cvt_pk_bf16_f32 v68, v68, v69
	v_cvt_pk_bf16_f32 v69, v70, v71
	v_mov_b32_e32 v146, v187
	s_nop 1
	v_permlane16_swap_b32_e32 v187, v146
	v_add_f32_e32 v187, v187, v146
	v_mov_b32_e32 v146, v187
	s_nop 1
	v_permlane32_swap_b32_e32 v187, v146
	v_add_f32_e32 v187, v187, v146
	s_waitcnt lgkmcnt(0)
	s_add_i32 s93, s76, 64
	s_mov_b32 m0, s16
	v_add_u32_e32 v164, s93, v231
	v_med3_i32 v164, v164, 0, s40
	v_lshl_or_b32 v164, v164, 7, v222
	global_load_lds_dwordx4 v164, s[24:25]
	s_add_i32 m0, s16, 0x400
	v_add_u32_e32 v165, s93, v232
	v_med3_i32 v165, v165, 0, s40
	v_lshl_or_b32 v165, v165, 7, v222
	global_load_lds_dwordx4 v165, s[24:25]
	s_waitcnt vmcnt(8)
	v_add_u32_e32 v154, s12, v225
	v_add_u32_e32 v155, s12, v226
	v_add_u32_e32 v156, s12, v227
	v_add_u32_e32 v157, s12, v228
	ds_read_b64_tr_b16 v[202:203], v154
	ds_read_b64_tr_b16 v[204:205], v155
	ds_read_b64_tr_b16 v[206:207], v156
	ds_read_b64_tr_b16 v[208:209], v157
	v_mfma_f32_16x16x16_bf16 v[96:99], v[88:89], v[0:1], 0
	v_mfma_f32_16x16x16_bf16 v[100:103], v[90:91], v[0:1], 0
	v_mfma_f32_16x16x16_bf16 v[104:107], v[92:93], v[0:1], 0
	v_mfma_f32_16x16x16_bf16 v[108:111], v[94:95], v[0:1], 0
	s_waitcnt lgkmcnt(0)
	s_add_i32 s93, s76, 0x80
	s_mov_b32 m0, s12
	v_add_u32_e32 v164, s93, v231
	v_med3_i32 v164, v164, 0, s40
	v_lshl_or_b32 v164, v164, 7, v222
	global_load_lds_dwordx4 v164, s[24:25]
	s_add_i32 m0, s12, 0x400
	v_add_u32_e32 v165, s93, v232
	v_med3_i32 v165, v165, 0, s40
	v_lshl_or_b32 v165, v165, 7, v222
	global_load_lds_dwordx4 v165, s[24:25]
	s_waitcnt vmcnt(8)
	v_add_u32_e32 v154, s13, v225
	v_add_u32_e32 v155, s13, v226
	v_add_u32_e32 v156, s13, v227
	v_add_u32_e32 v157, s13, v228
	ds_read_b64_tr_b16 v[88:89], v154
	ds_read_b64_tr_b16 v[90:91], v155
	ds_read_b64_tr_b16 v[92:93], v156
	ds_read_b64_tr_b16 v[94:95], v157
	v_mfma_f32_16x16x16_bf16 v[96:99], v[202:203], v[4:5], v[96:99]
	v_mfma_f32_16x16x16_bf16 v[112:115], v[202:203], v[36:37], 0
	v_mfma_f32_16x16x16_bf16 v[100:103], v[204:205], v[4:5], v[100:103]
	v_mfma_f32_16x16x16_bf16 v[116:119], v[204:205], v[36:37], 0
	v_mfma_f32_16x16x16_bf16 v[104:107], v[206:207], v[4:5], v[104:107]
	v_mfma_f32_16x16x16_bf16 v[120:123], v[206:207], v[36:37], 0
	v_mfma_f32_16x16x16_bf16 v[108:111], v[208:209], v[4:5], v[108:111]
	v_mfma_f32_16x16x16_bf16 v[124:127], v[208:209], v[36:37], 0
	s_waitcnt lgkmcnt(0)
	s_add_i32 s93, s76, 0xc0
	s_mov_b32 m0, s13
	v_add_u32_e32 v164, s93, v231
	v_med3_i32 v164, v164, 0, s40
	v_lshl_or_b32 v164, v164, 7, v222
	global_load_lds_dwordx4 v164, s[24:25]
	s_add_i32 m0, s13, 0x400
	v_add_u32_e32 v165, s93, v232
	v_med3_i32 v165, v165, 0, s40
	v_lshl_or_b32 v165, v165, 7, v222
	global_load_lds_dwordx4 v165, s[24:25]
	s_waitcnt vmcnt(8)
	v_add_u32_e32 v154, s14, v225
	v_add_u32_e32 v155, s14, v226
	v_add_u32_e32 v156, s14, v227
	v_add_u32_e32 v157, s14, v228
	ds_read_b64_tr_b16 v[202:203], v154
	ds_read_b64_tr_b16 v[204:205], v155
	ds_read_b64_tr_b16 v[206:207], v156
	ds_read_b64_tr_b16 v[208:209], v157
	v_mfma_f32_16x16x16_bf16 v[96:99], v[88:89], v[8:9], v[96:99]
	v_mfma_f32_16x16x16_bf16 v[112:115], v[88:89], v[40:41], v[112:115]
	v_mfma_f32_16x16x16_bf16 v[100:103], v[90:91], v[8:9], v[100:103]
	v_mfma_f32_16x16x16_bf16 v[116:119], v[90:91], v[40:41], v[116:119]
	v_mfma_f32_16x16x16_bf16 v[104:107], v[92:93], v[8:9], v[104:107]
	v_mfma_f32_16x16x16_bf16 v[120:123], v[92:93], v[40:41], v[120:123]
	v_mfma_f32_16x16x16_bf16 v[108:111], v[94:95], v[8:9], v[108:111]
	v_mfma_f32_16x16x16_bf16 v[124:127], v[94:95], v[40:41], v[124:127]
	s_waitcnt lgkmcnt(0)
	s_add_i32 s93, s76, 0x100
	s_mov_b32 m0, s14
	v_add_u32_e32 v164, s93, v231
	v_med3_i32 v164, v164, 0, s40
	v_lshl_or_b32 v164, v164, 7, v222
	global_load_lds_dwordx4 v164, s[24:25]
	s_add_i32 m0, s14, 0x400
	v_add_u32_e32 v165, s93, v232
	v_med3_i32 v165, v165, 0, s40
	v_lshl_or_b32 v165, v165, 7, v222
	global_load_lds_dwordx4 v165, s[24:25]
	s_waitcnt vmcnt(8)
	v_add_u32_e32 v154, s15, v225
	v_add_u32_e32 v155, s15, v226
	v_add_u32_e32 v156, s15, v227
	v_add_u32_e32 v157, s15, v228
	ds_read_b64_tr_b16 v[88:89], v154
	ds_read_b64_tr_b16 v[90:91], v155
	ds_read_b64_tr_b16 v[92:93], v156
	ds_read_b64_tr_b16 v[94:95], v157
	v_mfma_f32_16x16x16_bf16 v[96:99], v[202:203], v[12:13], v[96:99]
	v_mfma_f32_16x16x16_bf16 v[112:115], v[202:203], v[44:45], v[112:115]
	v_mfma_f32_16x16x16_bf16 v[100:103], v[204:205], v[12:13], v[100:103]
	v_mfma_f32_16x16x16_bf16 v[116:119], v[204:205], v[44:45], v[116:119]
	v_mfma_f32_16x16x16_bf16 v[104:107], v[206:207], v[12:13], v[104:107]
	v_mfma_f32_16x16x16_bf16 v[120:123], v[206:207], v[44:45], v[120:123]
	v_mfma_f32_16x16x16_bf16 v[108:111], v[208:209], v[12:13], v[108:111]
	v_mfma_f32_16x16x16_bf16 v[124:127], v[208:209], v[44:45], v[124:127]
	s_waitcnt lgkmcnt(0)
	s_add_i32 s93, s76, 0x140
	s_mov_b32 m0, s15
	v_add_u32_e32 v164, s93, v231
	v_med3_i32 v164, v164, 0, s40
	v_lshl_or_b32 v164, v164, 7, v222
	global_load_lds_dwordx4 v164, s[24:25]
	s_add_i32 m0, s15, 0x400
	v_add_u32_e32 v165, s93, v232
	v_med3_i32 v165, v165, 0, s40
	v_lshl_or_b32 v165, v165, 7, v222
	global_load_lds_dwordx4 v165, s[24:25]
	s_waitcnt vmcnt(8)
	v_add_u32_e32 v154, s16, v225
	v_add_u32_e32 v155, s16, v226
	v_add_u32_e32 v156, s16, v227
	v_add_u32_e32 v157, s16, v228
	ds_read_b64_tr_b16 v[202:203], v154
	ds_read_b64_tr_b16 v[204:205], v155
	ds_read_b64_tr_b16 v[206:207], v156
	ds_read_b64_tr_b16 v[208:209], v157
	v_mfma_f32_16x16x16_bf16 v[96:99], v[88:89], v[16:17], v[96:99]
	v_mfma_f32_16x16x16_bf16 v[112:115], v[88:89], v[48:49], v[112:115]
	v_mfma_f32_16x16x16_bf16 v[100:103], v[90:91], v[16:17], v[100:103]
	v_mfma_f32_16x16x16_bf16 v[116:119], v[90:91], v[48:49], v[116:119]
	v_mfma_f32_16x16x16_bf16 v[104:107], v[92:93], v[16:17], v[104:107]
	v_mfma_f32_16x16x16_bf16 v[120:123], v[92:93], v[48:49], v[120:123]
	v_mfma_f32_16x16x16_bf16 v[108:111], v[94:95], v[16:17], v[108:111]
	v_mfma_f32_16x16x16_bf16 v[124:127], v[94:95], v[48:49], v[124:127]
	s_waitcnt lgkmcnt(0)
	s_add_i32 s93, s79, 0
	s_mov_b32 m0, s16
	v_add_u32_e32 v164, s93, v162
	v_lshl_or_b32 v164, v164, 7, v220
	global_load_lds_dwordx4 v164, s[18:19]
	s_add_i32 m0, s16, 0x400
	v_add_u32_e32 v165, s93, v163
	v_lshl_or_b32 v165, v165, 7, v221
	global_load_lds_dwordx4 v165, s[18:19]
	s_waitcnt vmcnt(8)
	v_add_u32_e32 v154, s12, v225
	v_add_u32_e32 v155, s12, v226
	v_add_u32_e32 v156, s12, v227
	v_add_u32_e32 v157, s12, v228
	ds_read_b64_tr_b16 v[88:89], v154
	ds_read_b64_tr_b16 v[90:91], v155
	ds_read_b64_tr_b16 v[92:93], v156
	ds_read_b64_tr_b16 v[94:95], v157
	v_mfma_f32_16x16x16_bf16 v[96:99], v[202:203], v[20:21], v[96:99]
	v_mfma_f32_16x16x16_bf16 v[112:115], v[202:203], v[52:53], v[112:115]
	v_mfma_f32_16x16x16_bf16 v[100:103], v[204:205], v[20:21], v[100:103]
	v_mfma_f32_16x16x16_bf16 v[116:119], v[204:205], v[52:53], v[116:119]
	v_mfma_f32_16x16x16_bf16 v[104:107], v[206:207], v[20:21], v[104:107]
	v_mfma_f32_16x16x16_bf16 v[120:123], v[206:207], v[52:53], v[120:123]
	v_mfma_f32_16x16x16_bf16 v[108:111], v[208:209], v[20:21], v[108:111]
	v_mfma_f32_16x16x16_bf16 v[124:127], v[208:209], v[52:53], v[124:127]
	s_waitcnt lgkmcnt(0)
	s_add_i32 s93, s79, 0xfffffc00
	s_mov_b32 m0, s12
	v_add_u32_e32 v164, s93, v162
	v_med3_i32 v164, v164, 0, s40
	v_lshl_or_b32 v164, v164, 7, v220
	global_load_lds_dwordx4 v164, s[20:21]
	s_add_i32 m0, s12, 0x400
	v_add_u32_e32 v165, s93, v163
	v_med3_i32 v165, v165, 0, s40
	v_lshl_or_b32 v165, v165, 7, v221
	global_load_lds_dwordx4 v165, s[20:21]
	s_waitcnt vmcnt(8)
	v_add_u32_e32 v154, s13, v225
	v_add_u32_e32 v155, s13, v226
	v_add_u32_e32 v156, s13, v227
	v_add_u32_e32 v157, s13, v228
	ds_read_b64_tr_b16 v[202:203], v154
	ds_read_b64_tr_b16 v[204:205], v155
	ds_read_b64_tr_b16 v[206:207], v156
	ds_read_b64_tr_b16 v[208:209], v157
	v_mfma_f32_16x16x16_bf16 v[96:99], v[88:89], v[24:25], v[96:99]
	v_mfma_f32_16x16x16_bf16 v[112:115], v[88:89], v[56:57], v[112:115]
	v_mfma_f32_16x16x16_bf16 v[100:103], v[90:91], v[24:25], v[100:103]
	v_mfma_f32_16x16x16_bf16 v[116:119], v[90:91], v[56:57], v[116:119]
	v_mfma_f32_16x16x16_bf16 v[104:107], v[92:93], v[24:25], v[104:107]
	v_mfma_f32_16x16x16_bf16 v[120:123], v[92:93], v[56:57], v[120:123]
	v_mfma_f32_16x16x16_bf16 v[108:111], v[94:95], v[24:25], v[108:111]
	v_mfma_f32_16x16x16_bf16 v[124:127], v[94:95], v[56:57], v[124:127]
	s_waitcnt lgkmcnt(0)
	s_add_i32 s93, s79, 0xfffffd00
	s_mov_b32 m0, s13
	v_add_u32_e32 v164, s93, v162
	v_med3_i32 v164, v164, 0, s40
	v_lshl_or_b32 v164, v164, 7, v220
	global_load_lds_dwordx4 v164, s[20:21]
	s_add_i32 m0, s13, 0x400
	v_add_u32_e32 v165, s93, v163
	v_med3_i32 v165, v165, 0, s40
	v_lshl_or_b32 v165, v165, 7, v221
	global_load_lds_dwordx4 v165, s[20:21]
	s_waitcnt vmcnt(8)
	v_add_u32_e32 v154, s14, v225
	v_add_u32_e32 v155, s14, v226
	v_add_u32_e32 v156, s14, v227
	v_add_u32_e32 v157, s14, v228
	ds_read_b64_tr_b16 v[88:89], v154
	ds_read_b64_tr_b16 v[90:91], v155
	ds_read_b64_tr_b16 v[92:93], v156
	ds_read_b64_tr_b16 v[94:95], v157
	v_mfma_f32_16x16x16_bf16 v[96:99], v[202:203], v[28:29], v[96:99]
	v_mfma_f32_16x16x16_bf16 v[112:115], v[202:203], v[60:61], v[112:115]
	v_mfma_f32_16x16x16_bf16 v[100:103], v[204:205], v[28:29], v[100:103]
	v_mfma_f32_16x16x16_bf16 v[116:119], v[204:205], v[60:61], v[116:119]
	v_mfma_f32_16x16x16_bf16 v[104:107], v[206:207], v[28:29], v[104:107]
	v_mfma_f32_16x16x16_bf16 v[120:123], v[206:207], v[60:61], v[120:123]
	v_mfma_f32_16x16x16_bf16 v[108:111], v[208:209], v[28:29], v[108:111]
	v_mfma_f32_16x16x16_bf16 v[124:127], v[208:209], v[60:61], v[124:127]
	s_waitcnt lgkmcnt(0)
	s_add_i32 s93, s79, 0xfffffe00
	s_mov_b32 m0, s14
	v_add_u32_e32 v164, s93, v162
	v_med3_i32 v164, v164, 0, s40
	v_lshl_or_b32 v164, v164, 7, v220
	global_load_lds_dwordx4 v164, s[20:21]
	s_add_i32 m0, s14, 0x400
	v_add_u32_e32 v165, s93, v163
	v_med3_i32 v165, v165, 0, s40
	v_lshl_or_b32 v165, v165, 7, v221
	global_load_lds_dwordx4 v165, s[20:21]
	s_waitcnt vmcnt(8)
	v_add_u32_e32 v154, s15, v225
	v_add_u32_e32 v155, s15, v226
	v_add_u32_e32 v156, s15, v227
	v_add_u32_e32 v157, s15, v228
	ds_read_b64_tr_b16 v[202:203], v154
	ds_read_b64_tr_b16 v[204:205], v155
	ds_read_b64_tr_b16 v[206:207], v156
	ds_read_b64_tr_b16 v[208:209], v157
	v_mfma_f32_16x16x16_bf16 v[96:99], v[88:89], v[32:33], v[96:99]
	v_mfma_f32_16x16x16_bf16 v[112:115], v[88:89], v[64:65], v[112:115]
	v_mfma_f32_16x16x16_bf16 v[100:103], v[90:91], v[32:33], v[100:103]
	v_mfma_f32_16x16x16_bf16 v[116:119], v[90:91], v[64:65], v[116:119]
	v_mfma_f32_16x16x16_bf16 v[104:107], v[92:93], v[32:33], v[104:107]
	v_mfma_f32_16x16x16_bf16 v[120:123], v[92:93], v[64:65], v[120:123]
	v_mfma_f32_16x16x16_bf16 v[108:111], v[94:95], v[32:33], v[108:111]
	v_mfma_f32_16x16x16_bf16 v[124:127], v[94:95], v[64:65], v[124:127]
	s_waitcnt lgkmcnt(0)
	s_add_i32 s93, s79, 0xffffff00
	s_mov_b32 m0, s15
	v_add_u32_e32 v164, s93, v162
	v_med3_i32 v164, v164, 0, s40
	v_lshl_or_b32 v164, v164, 7, v220
	global_load_lds_dwordx4 v164, s[20:21]
	s_add_i32 m0, s15, 0x400
	v_add_u32_e32 v165, s93, v163
	v_med3_i32 v165, v165, 0, s40
	v_lshl_or_b32 v165, v165, 7, v221
	global_load_lds_dwordx4 v165, s[20:21]
	v_mfma_f32_16x16x16_bf16 v[112:115], v[202:203], v[68:69], v[112:115]
	v_mfma_f32_16x16x16_bf16 v[116:119], v[204:205], v[68:69], v[116:119]
	v_mfma_f32_16x16x16_bf16 v[120:123], v[206:207], v[68:69], v[120:123]
	v_mfma_f32_16x16x16_bf16 v[124:127], v[208:209], v[68:69], v[124:127]
	s_waitcnt lgkmcnt(0)
	v_max_f32_e32 v146, v144, v184
	v_sub_f32_e32 v148, v144, v146
	v_sub_f32_e32 v150, v184, v146
	v_exp_f32_e32 v148, v148
	v_exp_f32_e32 v150, v150
	v_mov_b32_e32 v184, v146
	v_mul_f32_e32 v185, v185, v150
	v_fmac_f32_e32 v185, v145, v148
	v_pk_mul_f32 v[96:97], v[150:151], v[96:97] op_sel_hi:[0,1]
	v_pk_mul_f32 v[98:99], v[150:151], v[98:99] op_sel_hi:[0,1]
	v_pk_mul_f32 v[100:101], v[150:151], v[100:101] op_sel_hi:[0,1]
	v_pk_mul_f32 v[102:103], v[150:151], v[102:103] op_sel_hi:[0,1]
	v_pk_mul_f32 v[104:105], v[150:151], v[104:105] op_sel_hi:[0,1]
	v_pk_mul_f32 v[106:107], v[150:151], v[106:107] op_sel_hi:[0,1]
	v_pk_mul_f32 v[108:109], v[150:151], v[108:109] op_sel_hi:[0,1]
	v_pk_mul_f32 v[110:111], v[150:151], v[110:111] op_sel_hi:[0,1]
	v_pk_fma_f32 v[96:97], v[148:149], v[128:129], v[96:97] op_sel_hi:[0,1,1]
	v_pk_fma_f32 v[98:99], v[148:149], v[130:131], v[98:99] op_sel_hi:[0,1,1]
	v_pk_fma_f32 v[100:101], v[148:149], v[132:133], v[100:101] op_sel_hi:[0,1,1]
	v_pk_fma_f32 v[102:103], v[148:149], v[134:135], v[102:103] op_sel_hi:[0,1,1]
	v_pk_fma_f32 v[104:105], v[148:149], v[136:137], v[104:105] op_sel_hi:[0,1,1]
	v_pk_fma_f32 v[106:107], v[148:149], v[138:139], v[106:107] op_sel_hi:[0,1,1]
	v_pk_fma_f32 v[108:109], v[148:149], v[140:141], v[108:109] op_sel_hi:[0,1,1]
	v_pk_fma_f32 v[110:111], v[148:149], v[142:143], v[110:111] op_sel_hi:[0,1,1]
	s_and_saveexec_b64 s[80:81], s[74:75]
	ds_write_b64 v194, v[184:185]
	s_mov_b64 exec, s[80:81]
	ds_write_b128 v190, v[96:99]
	ds_write_b128 v191, v[100:103]
	ds_write_b128 v192, v[104:107]
	ds_write_b128 v193, v[108:111]
	s_waitcnt lgkmcnt(0)
	v_max_f32_e32 v146, v182, v186
	v_sub_f32_e32 v148, v182, v146
	v_sub_f32_e32 v150, v186, v146
	v_exp_f32_e32 v148, v148
	v_exp_f32_e32 v150, v150
	v_mov_b32_e32 v186, v146
	v_mul_f32_e32 v187, v187, v150
	v_fmac_f32_e32 v187, v183, v148
	v_pk_mul_f32 v[112:113], v[150:151], v[112:113] op_sel_hi:[0,1]
	v_pk_mul_f32 v[114:115], v[150:151], v[114:115] op_sel_hi:[0,1]
	v_pk_mul_f32 v[116:117], v[150:151], v[116:117] op_sel_hi:[0,1]
	v_pk_mul_f32 v[118:119], v[150:151], v[118:119] op_sel_hi:[0,1]
	v_pk_mul_f32 v[120:121], v[150:151], v[120:121] op_sel_hi:[0,1]
	v_pk_mul_f32 v[122:123], v[150:151], v[122:123] op_sel_hi:[0,1]
	v_pk_mul_f32 v[124:125], v[150:151], v[124:125] op_sel_hi:[0,1]
	v_pk_mul_f32 v[126:127], v[150:151], v[126:127] op_sel_hi:[0,1]
	v_pk_fma_f32 v[112:113], v[148:149], v[166:167], v[112:113] op_sel_hi:[0,1,1]
	v_pk_fma_f32 v[114:115], v[148:149], v[168:169], v[114:115] op_sel_hi:[0,1,1]
	v_pk_fma_f32 v[116:117], v[148:149], v[170:171], v[116:117] op_sel_hi:[0,1,1]
	v_pk_fma_f32 v[118:119], v[148:149], v[172:173], v[118:119] op_sel_hi:[0,1,1]
	v_pk_fma_f32 v[120:121], v[148:149], v[174:175], v[120:121] op_sel_hi:[0,1,1]
	v_pk_fma_f32 v[122:123], v[148:149], v[176:177], v[122:123] op_sel_hi:[0,1,1]
	v_pk_fma_f32 v[124:125], v[148:149], v[178:179], v[124:125] op_sel_hi:[0,1,1]
	v_pk_fma_f32 v[126:127], v[148:149], v[180:181], v[126:127] op_sel_hi:[0,1,1]
	s_and_saveexec_b64 s[80:81], s[74:75]
	ds_write_b64 v199, v[186:187]
	s_mov_b64 exec, s[80:81]
	ds_write_b128 v195, v[112:115]
	ds_write_b128 v196, v[116:119]
	ds_write_b128 v197, v[120:123]
	ds_write_b128 v198, v[124:127]
	s_waitcnt lgkmcnt(0)
	s_barrier
	s_add_i32 s76, s38, s84
	s_add_i32 s79, s39, s82
	v_lshlrev_b32_e32 v231, 4, v218
	v_add_u32_e32 v232, 8, v218
	v_lshlrev_b32_e32 v232, 4, v232
	v_lshlrev_b32_e32 v162, 0, v218
	v_add_u32_e32 v163, 8, v218
	v_lshlrev_b32_e32 v163, 0, v163
	s_add_i32 s8, s38, s85
	s_waitcnt vmcnt(8)
	v_add_u32_e32 v154, s16, v223
	v_add_u32_e32 v155, s16, v224
	ds_read_b128 v[72:75], v154
	ds_read_b128 v[76:79], v155
	s_waitcnt lgkmcnt(0)
	s_add_i32 s93, s76, 0
	s_mov_b32 m0, s16
	v_add_u32_e32 v164, s93, v231
	v_med3_i32 v164, v164, 0, s40
	v_lshl_or_b32 v164, v164, 7, v220
	global_load_lds_dwordx4 v164, s[20:21]
	s_add_i32 m0, s16, 0x400
	v_add_u32_e32 v165, s93, v232
	v_med3_i32 v165, v165, 0, s40
	v_lshl_or_b32 v165, v165, 7, v221
	global_load_lds_dwordx4 v165, s[20:21]
	s_waitcnt vmcnt(8)
	v_add_u32_e32 v154, s12, v223
	v_add_u32_e32 v155, s12, v224
	ds_read_b128 v[202:205], v154
	ds_read_b128 v[206:209], v155
	s_waitcnt lgkmcnt(0)
	s_add_i32 s93, s76, 0x100
	s_mov_b32 m0, s12
	v_add_u32_e32 v164, s93, v231
	v_med3_i32 v164, v164, 0, s40
	v_lshl_or_b32 v164, v164, 7, v220
	global_load_lds_dwordx4 v164, s[20:21]
	s_add_i32 m0, s12, 0x400
	v_add_u32_e32 v165, s93, v232
	v_med3_i32 v165, v165, 0, s40
	v_lshl_or_b32 v165, v165, 7, v221
	global_load_lds_dwordx4 v165, s[20:21]
	s_waitcnt vmcnt(8)
	v_add_u32_e32 v154, s13, v223
	v_add_u32_e32 v155, s13, v224
	ds_read_b128 v[88:91], v154
	ds_read_b128 v[92:95], v155
	v_mfma_f32_16x16x32_bf16 v[0:3], v[202:205], v[72:75], 0
	v_mfma_f32_16x16x32_bf16 v[0:3], v[206:209], v[76:79], v[0:3]
	s_waitcnt lgkmcnt(0)
	s_add_i32 s93, s76, 0x200
	s_mov_b32 m0, s13
	v_add_u32_e32 v164, s93, v231
	v_med3_i32 v164, v164, 0, s40
	v_lshl_or_b32 v164, v164, 7, v220
	global_load_lds_dwordx4 v164, s[20:21]
	s_add_i32 m0, s13, 0x400
	v_add_u32_e32 v165, s93, v232
	v_med3_i32 v165, v165, 0, s40
	v_lshl_or_b32 v165, v165, 7, v221
	global_load_lds_dwordx4 v165, s[20:21]
	s_waitcnt vmcnt(8)
	v_add_u32_e32 v154, s14, v223
	v_add_u32_e32 v155, s14, v224
	ds_read_b128 v[202:205], v154
	ds_read_b128 v[206:209], v155
	v_mfma_f32_16x16x32_bf16 v[4:7], v[88:91], v[72:75], 0
	v_mfma_f32_16x16x32_bf16 v[4:7], v[92:95], v[76:79], v[4:7]
	s_waitcnt lgkmcnt(0)
	s_add_i32 s93, s76, 0x300
	s_mov_b32 m0, s14
	v_add_u32_e32 v164, s93, v231
	v_med3_i32 v164, v164, 0, s40
	v_lshl_or_b32 v164, v164, 7, v220
	global_load_lds_dwordx4 v164, s[20:21]
	s_add_i32 m0, s14, 0x400
	v_add_u32_e32 v165, s93, v232
	v_med3_i32 v165, v165, 0, s40
	v_lshl_or_b32 v165, v165, 7, v221
	global_load_lds_dwordx4 v165, s[20:21]
	s_waitcnt vmcnt(8)
	v_add_u32_e32 v154, s15, v223
	v_add_u32_e32 v155, s15, v224
	ds_read_b128 v[88:91], v154
	ds_read_b128 v[92:95], v155
	v_mfma_f32_16x16x32_bf16 v[8:11], v[202:205], v[72:75], 0
	v_mfma_f32_16x16x32_bf16 v[8:11], v[206:209], v[76:79], v[8:11]
	s_waitcnt lgkmcnt(0)
	s_add_i32 s93, s76, 0x400
	s_mov_b32 m0, s15
	v_add_u32_e32 v164, s93, v231
	v_med3_i32 v164, v164, 0, s40
	v_lshl_or_b32 v164, v164, 7, v220
	global_load_lds_dwordx4 v164, s[20:21]
	s_add_i32 m0, s15, 0x400
	v_add_u32_e32 v165, s93, v232
	v_med3_i32 v165, v165, 0, s40
	v_lshl_or_b32 v165, v165, 7, v221
	global_load_lds_dwordx4 v165, s[20:21]
	s_waitcnt vmcnt(8)
	v_add_u32_e32 v154, s16, v223
	v_add_u32_e32 v155, s16, v224
	ds_read_b128 v[202:205], v154
	ds_read_b128 v[206:209], v155
	v_mfma_f32_16x16x32_bf16 v[12:15], v[88:91], v[72:75], 0
	v_mfma_f32_16x16x32_bf16 v[12:15], v[92:95], v[76:79], v[12:15]
	s_waitcnt lgkmcnt(0)
	s_add_i32 s93, s8, 0
	s_mov_b32 m0, s16
	v_add_u32_e32 v164, s93, v231
	v_lshl_or_b32 v164, v164, 7, v220
	global_load_lds_dwordx4 v164, s[18:19]
	s_add_i32 m0, s16, 0x400
	v_add_u32_e32 v165, s93, v232
	v_lshl_or_b32 v165, v165, 7, v221
	global_load_lds_dwordx4 v165, s[18:19]
	s_waitcnt vmcnt(8)
	v_add_u32_e32 v154, s12, v223
	v_add_u32_e32 v155, s12, v224
	ds_read_b128 v[88:91], v154
	ds_read_b128 v[92:95], v155
	v_mfma_f32_16x16x32_bf16 v[16:19], v[202:205], v[72:75], 0
	v_mfma_f32_16x16x32_bf16 v[16:19], v[206:209], v[76:79], v[16:19]
	s_waitcnt lgkmcnt(0)
	s_add_i32 s93, s8, 0xfffffc00
	s_mov_b32 m0, s12
	v_add_u32_e32 v164, s93, v231
	v_med3_i32 v164, v164, 0, s40
	v_lshl_or_b32 v164, v164, 7, v220
	global_load_lds_dwordx4 v164, s[20:21]
	s_add_i32 m0, s12, 0x400
	v_add_u32_e32 v165, s93, v232
	v_med3_i32 v165, v165, 0, s40
	v_lshl_or_b32 v165, v165, 7, v221
	global_load_lds_dwordx4 v165, s[20:21]
	s_waitcnt vmcnt(8)
	v_add_u32_e32 v154, s13, v223
	v_add_u32_e32 v155, s13, v224
	ds_read_b128 v[202:205], v154
	ds_read_b128 v[206:209], v155
	v_mfma_f32_16x16x32_bf16 v[20:23], v[88:91], v[72:75], 0
	v_mfma_f32_16x16x32_bf16 v[20:23], v[92:95], v[76:79], v[20:23]
	s_waitcnt lgkmcnt(0)
	s_add_i32 s93, s8, 0xfffffd00
	s_mov_b32 m0, s13
	v_add_u32_e32 v164, s93, v231
	v_med3_i32 v164, v164, 0, s40
	v_lshl_or_b32 v164, v164, 7, v220
	global_load_lds_dwordx4 v164, s[20:21]
	s_add_i32 m0, s13, 0x400
	v_add_u32_e32 v165, s93, v232
	v_med3_i32 v165, v165, 0, s40
	v_lshl_or_b32 v165, v165, 7, v221
	global_load_lds_dwordx4 v165, s[20:21]
	s_waitcnt vmcnt(8)
	v_add_u32_e32 v154, s14, v223
	v_add_u32_e32 v155, s14, v224
	ds_read_b128 v[88:91], v154
	ds_read_b128 v[92:95], v155
	v_mfma_f32_16x16x32_bf16 v[24:27], v[202:205], v[72:75], 0
	v_mfma_f32_16x16x32_bf16 v[24:27], v[206:209], v[76:79], v[24:27]
	s_waitcnt lgkmcnt(0)
	s_add_i32 s93, s8, 0xfffffe00
	s_mov_b32 m0, s14
	v_add_u32_e32 v164, s93, v231
	v_med3_i32 v164, v164, 0, s40
	v_lshl_or_b32 v164, v164, 7, v220
	global_load_lds_dwordx4 v164, s[20:21]
	s_add_i32 m0, s14, 0x400
	v_add_u32_e32 v165, s93, v232
	v_med3_i32 v165, v165, 0, s40
	v_lshl_or_b32 v165, v165, 7, v221
	global_load_lds_dwordx4 v165, s[20:21]
	s_waitcnt vmcnt(8)
	v_add_u32_e32 v154, s15, v223
	v_add_u32_e32 v155, s15, v224
	ds_read_b128 v[202:205], v154
	ds_read_b128 v[206:209], v155
	v_mfma_f32_16x16x32_bf16 v[28:31], v[88:91], v[72:75], 0
	v_mfma_f32_16x16x32_bf16 v[28:31], v[92:95], v[76:79], v[28:31]
	s_waitcnt lgkmcnt(0)
	s_add_i32 s93, s8, 0xffffff00
	s_mov_b32 m0, s15
	v_add_u32_e32 v164, s93, v231
	v_med3_i32 v164, v164, 0, s40
	v_lshl_or_b32 v164, v164, 7, v220
	global_load_lds_dwordx4 v164, s[20:21]
	s_add_i32 m0, s15, 0x400
	v_add_u32_e32 v165, s93, v232
	v_med3_i32 v165, v165, 0, s40
	v_lshl_or_b32 v165, v165, 7, v221
	global_load_lds_dwordx4 v165, s[20:21]
	s_waitcnt vmcnt(8)
	v_add_u32_e32 v154, s16, v223
	v_add_u32_e32 v155, s16, v224
	ds_read_b128 v[80:83], v154
	ds_read_b128 v[84:87], v155
	v_mfma_f32_16x16x32_bf16 v[32:35], v[202:205], v[72:75], 0
	v_mfma_f32_16x16x32_bf16 v[32:35], v[206:209], v[76:79], v[32:35]
	s_waitcnt lgkmcnt(0)
	s_add_i32 s93, s8, 0
	s_mov_b32 m0, s16
	v_add_u32_e32 v164, s93, v231
	v_med3_i32 v164, v164, 0, s40
	v_lshl_or_b32 v164, v164, 7, v220
	global_load_lds_dwordx4 v164, s[20:21]
	s_add_i32 m0, s16, 0x400
	v_add_u32_e32 v165, s93, v232
	v_med3_i32 v165, v165, 0, s40
	v_lshl_or_b32 v165, v165, 7, v221
	global_load_lds_dwordx4 v165, s[20:21]
	s_waitcnt vmcnt(8)
	v_add_u32_e32 v154, s12, v223
	v_add_u32_e32 v155, s12, v224
	ds_read_b128 v[202:205], v154
	ds_read_b128 v[206:209], v155
	v_mov_b32_e32 v188, s84
	v_lshl_add_u32 v188, v216, 4, v188
	v_lshrrev_b32_e32 v146, 4, v188
	v_xor_b32_e32 v146, v146, v188
	v_and_b32_e32 v146, 15, v146
	v_lshlrev_b32_e32 v147, 8, v188
	v_or_b32_e32 v148, 0, v217
	v_xor_b32_e32 v148, v148, v146
	v_lshl_add_u32 v190, v148, 4, v147
	v_or_b32_e32 v148, 4, v217
	v_xor_b32_e32 v148, v148, v146
	v_lshl_add_u32 v191, v148, 4, v147
	v_or_b32_e32 v148, 8, v217
	v_xor_b32_e32 v148, v148, v146
	v_lshl_add_u32 v192, v148, 4, v147
	v_or_b32_e32 v148, 12, v217
	v_xor_b32_e32 v148, v148, v146
	v_lshl_add_u32 v193, v148, 4, v147
	v_lshlrev_b32_e32 v194, 3, v188
	v_add_u32_e32 v194, 0x10000, v194
	ds_read_b64 v[144:145], v194
	ds_read_b128 v[128:131], v190
	ds_read_b128 v[132:135], v191
	ds_read_b128 v[136:139], v192
	ds_read_b128 v[140:143], v193
	s_ashr_i32 s77, s76, 4
	s_sub_i32 s77, 64, s77
	s_sub_i32 s78, s40, s76
	s_waitcnt lgkmcnt(0)
	s_add_i32 s93, s8, 0x100
	s_mov_b32 m0, s12
	v_add_u32_e32 v164, s93, v231
	v_med3_i32 v164, v164, 0, s40
	v_lshl_or_b32 v164, v164, 7, v220
	global_load_lds_dwordx4 v164, s[20:21]
	s_add_i32 m0, s12, 0x400
	v_add_u32_e32 v165, s93, v232
	v_med3_i32 v165, v165, 0, s40
	v_lshl_or_b32 v165, v165, 7, v221
	global_load_lds_dwordx4 v165, s[20:21]
	s_waitcnt vmcnt(8)
	v_add_u32_e32 v154, s13, v223
	v_add_u32_e32 v155, s13, v224
	ds_read_b128 v[88:91], v154
	ds_read_b128 v[92:95], v155
	v_mfma_f32_16x16x32_bf16 v[36:39], v[202:205], v[80:83], 0
	v_mfma_f32_16x16x32_bf16 v[36:39], v[206:209], v[84:87], v[36:39]
	s_ashr_i32 s78, s78, 4
	s_add_i32 s78, s78, 64
	v_cndmask_b32_e64 v0, v0, v230, s[52:53]
	v_cndmask_b32_e64 v32, v32, v230, s[62:63]
	v_cndmask_b32_e64 v1, v1, v230, s[56:57]
	v_cndmask_b32_e64 v33, v33, v230, s[64:65]
	v_cndmask_b32_e64 v2, v2, v230, s[58:59]
	v_cndmask_b32_e64 v34, v34, v230, s[70:71]
	v_cndmask_b32_e64 v3, v3, v230, s[60:61]
	v_cndmask_b32_e64 v35, v35, v230, s[72:73]
	v_sub_u32_e32 v200, s77, v229
	s_sub_i32 s91, s78, s77
	v_sub_u32_e32 v150, 0, v200
	v_sub_u32_e32 v151, 1, v200
	v_sub_u32_e32 v152, 2, v200
	v_sub_u32_e32 v153, 3, v200
	v_cmp_lt_u32_e64 s[94:95], s91, v150
	v_cmp_lt_u32_e64 s[86:87], s91, v151
	v_cmp_lt_u32_e64 s[0:1], s91, v152
	v_cmp_lt_u32_e64 s[2:3], s91, v153
	v_cndmask_b32_e64 v0, v0, v230, s[94:95]
	v_cndmask_b32_e64 v1, v1, v230, s[86:87]
	v_cndmask_b32_e64 v2, v2, v230, s[0:1]
	v_cndmask_b32_e64 v3, v3, v230, s[2:3]
	v_sub_u32_e32 v150, 16, v200
	v_sub_u32_e32 v151, 17, v200
	v_sub_u32_e32 v152, 18, v200
	v_sub_u32_e32 v153, 19, v200
	s_waitcnt lgkmcnt(0)
	s_add_i32 s93, s8, 0x200
	s_mov_b32 m0, s13
	v_add_u32_e32 v164, s93, v231
	v_med3_i32 v164, v164, 0, s40
	v_lshl_or_b32 v164, v164, 7, v220
	global_load_lds_dwordx4 v164, s[20:21]
	s_add_i32 m0, s13, 0x400
	v_add_u32_e32 v165, s93, v232
	v_med3_i32 v165, v165, 0, s40
	v_lshl_or_b32 v165, v165, 7, v221
	global_load_lds_dwordx4 v165, s[20:21]
	s_waitcnt vmcnt(8)
	v_add_u32_e32 v154, s14, v223
	v_add_u32_e32 v155, s14, v224
	ds_read_b128 v[202:205], v154
	ds_read_b128 v[206:209], v155
	v_mfma_f32_16x16x32_bf16 v[40:43], v[88:91], v[80:83], 0
	v_mfma_f32_16x16x32_bf16 v[40:43], v[92:95], v[84:87], v[40:43]
	v_cmp_lt_u32_e64 s[94:95], s91, v150
	v_cmp_lt_u32_e64 s[86:87], s91, v151
	v_cmp_lt_u32_e64 s[0:1], s91, v152
	v_cmp_lt_u32_e64 s[2:3], s91, v153
	v_cndmask_b32_e64 v4, v4, v230, s[94:95]
	v_cndmask_b32_e64 v5, v5, v230, s[86:87]
	v_cndmask_b32_e64 v6, v6, v230, s[0:1]
	v_cndmask_b32_e64 v7, v7, v230, s[2:3]
	v_sub_u32_e32 v150, 32, v200
	v_sub_u32_e32 v151, 33, v200
	v_sub_u32_e32 v152, 34, v200
	v_sub_u32_e32 v153, 35, v200
	v_cmp_lt_u32_e64 s[94:95], s91, v150
	v_cmp_lt_u32_e64 s[86:87], s91, v151
	v_cmp_lt_u32_e64 s[0:1], s91, v152
	v_cmp_lt_u32_e64 s[2:3], s91, v153
	v_cndmask_b32_e64 v8, v8, v230, s[94:95]
	v_cndmask_b32_e64 v9, v9, v230, s[86:87]
	v_cndmask_b32_e64 v10, v10, v230, s[0:1]
	v_cndmask_b32_e64 v11, v11, v230, s[2:3]
	v_sub_u32_e32 v150, 48, v200
	v_sub_u32_e32 v151, 49, v200
	v_sub_u32_e32 v152, 50, v200
	v_sub_u32_e32 v153, 51, v200
	v_cmp_lt_u32_e64 s[94:95], s91, v150
	v_cmp_lt_u32_e64 s[86:87], s91, v151
	v_cmp_lt_u32_e64 s[0:1], s91, v152
	v_cmp_lt_u32_e64 s[2:3], s91, v153
	s_waitcnt lgkmcnt(0)
	s_add_i32 s93, s8, 0x300
	s_mov_b32 m0, s14
	v_add_u32_e32 v164, s93, v231
	v_med3_i32 v164, v164, 0, s40
	v_lshl_or_b32 v164, v164, 7, v220
	global_load_lds_dwordx4 v164, s[20:21]
	s_add_i32 m0, s14, 0x400
	v_add_u32_e32 v165, s93, v232
	v_med3_i32 v165, v165, 0, s40
	v_lshl_or_b32 v165, v165, 7, v221
	global_load_lds_dwordx4 v165, s[20:21]
	s_waitcnt vmcnt(8)
	v_add_u32_e32 v154, s15, v223
	v_add_u32_e32 v155, s15, v224
	ds_read_b128 v[88:91], v154
	ds_read_b128 v[92:95], v155
	v_mfma_f32_16x16x32_bf16 v[44:47], v[202:205], v[80:83], 0
	v_mfma_f32_16x16x32_bf16 v[44:47], v[206:209], v[84:87], v[44:47]
	v_cndmask_b32_e64 v12, v12, v230, s[94:95]
	v_cndmask_b32_e64 v13, v13, v230, s[86:87]
	v_cndmask_b32_e64 v14, v14, v230, s[0:1]
	v_cndmask_b32_e64 v15, v15, v230, s[2:3]
	v_sub_u32_e32 v150, 64, v200
	v_sub_u32_e32 v151, 0x41, v200
	v_sub_u32_e32 v152, 0x42, v200
	v_sub_u32_e32 v153, 0x43, v200
	v_cmp_lt_u32_e64 s[94:95], s91, v150
	v_cmp_lt_u32_e64 s[86:87], s91, v151
	v_cmp_lt_u32_e64 s[0:1], s91, v152
	v_cmp_lt_u32_e64 s[2:3], s91, v153
	v_cndmask_b32_e64 v16, v16, v230, s[94:95]
	v_cndmask_b32_e64 v17, v17, v230, s[86:87]
	v_cndmask_b32_e64 v18, v18, v230, s[0:1]
	v_cndmask_b32_e64 v19, v19, v230, s[2:3]
	v_sub_u32_e32 v150, 0x50, v200
	v_sub_u32_e32 v151, 0x51, v200
	v_sub_u32_e32 v152, 0x52, v200
	v_sub_u32_e32 v153, 0x53, v200
	v_cmp_lt_u32_e64 s[94:95], s91, v150
	v_cmp_lt_u32_e64 s[86:87], s91, v151
	v_cmp_lt_u32_e64 s[0:1], s91, v152
	v_cmp_lt_u32_e64 s[2:3], s91, v153
	v_cndmask_b32_e64 v20, v20, v230, s[94:95]
	v_cndmask_b32_e64 v21, v21, v230, s[86:87]
	v_cndmask_b32_e64 v22, v22, v230, s[0:1]
	v_cndmask_b32_e64 v23, v23, v230, s[2:3]
	s_waitcnt lgkmcnt(0)
	s_add_i32 s93, s8, 0x400
	s_mov_b32 m0, s15
	v_add_u32_e32 v164, s93, v231
	v_med3_i32 v164, v164, 0, s40
	v_lshl_or_b32 v164, v164, 7, v220
	global_load_lds_dwordx4 v164, s[20:21]
	s_add_i32 m0, s15, 0x400
	v_add_u32_e32 v165, s93, v232
	v_med3_i32 v165, v165, 0, s40
	v_lshl_or_b32 v165, v165, 7, v221
	global_load_lds_dwordx4 v165, s[20:21]
	s_waitcnt vmcnt(8)
	v_add_u32_e32 v154, s16, v223
	v_add_u32_e32 v155, s16, v224
	ds_read_b128 v[202:205], v154
	ds_read_b128 v[206:209], v155
	v_mfma_f32_16x16x32_bf16 v[48:51], v[88:91], v[80:83], 0
	v_mfma_f32_16x16x32_bf16 v[48:51], v[92:95], v[84:87], v[48:51]
	v_sub_u32_e32 v150, 0x60, v200
	v_sub_u32_e32 v151, 0x61, v200
	v_sub_u32_e32 v152, 0x62, v200
	v_sub_u32_e32 v153, 0x63, v200
	v_cmp_lt_u32_e64 s[94:95], s91, v150
	v_cmp_lt_u32_e64 s[86:87], s91, v151
	v_cmp_lt_u32_e64 s[0:1], s91, v152
	v_cmp_lt_u32_e64 s[2:3], s91, v153
	v_cndmask_b32_e64 v24, v24, v230, s[94:95]
	v_cndmask_b32_e64 v25, v25, v230, s[86:87]
	v_cndmask_b32_e64 v26, v26, v230, s[0:1]
	v_cndmask_b32_e64 v27, v27, v230, s[2:3]
	v_sub_u32_e32 v150, 0x70, v200
	v_sub_u32_e32 v151, 0x71, v200
	v_sub_u32_e32 v152, 0x72, v200
	v_sub_u32_e32 v153, 0x73, v200
	v_cmp_lt_u32_e64 s[94:95], s91, v150
	v_cmp_lt_u32_e64 s[86:87], s91, v151
	v_cmp_lt_u32_e64 s[0:1], s91, v152
	v_cmp_lt_u32_e64 s[2:3], s91, v153
	v_cndmask_b32_e64 v28, v28, v230, s[94:95]
	v_cndmask_b32_e64 v29, v29, v230, s[86:87]
	v_cndmask_b32_e64 v30, v30, v230, s[0:1]
	v_cndmask_b32_e64 v31, v31, v230, s[2:3]
	v_sub_u32_e32 v150, 0x80, v200
	v_sub_u32_e32 v151, 0x81, v200
	v_sub_u32_e32 v152, 0x82, v200
	v_sub_u32_e32 v153, 0x83, v200
	s_waitcnt lgkmcnt(0)
	s_add_i32 s93, s76, 0xfffffc00
	s_mov_b32 m0, s16
	v_add_u32_e32 v164, s93, v231
	v_med3_i32 v164, v164, 0, s40
	v_lshl_or_b32 v164, v164, 7, v222
	global_load_lds_dwordx4 v164, s[24:25]
	s_add_i32 m0, s16, 0x400
	v_add_u32_e32 v165, s93, v232
	v_med3_i32 v165, v165, 0, s40
	v_lshl_or_b32 v165, v165, 7, v222
	global_load_lds_dwordx4 v165, s[24:25]
	s_waitcnt vmcnt(8)
	v_add_u32_e32 v154, s12, v223
	v_add_u32_e32 v155, s12, v224
	ds_read_b128 v[88:91], v154
	ds_read_b128 v[92:95], v155
	v_mfma_f32_16x16x32_bf16 v[52:55], v[202:205], v[80:83], 0
	v_mfma_f32_16x16x32_bf16 v[52:55], v[206:209], v[84:87], v[52:55]
	v_cmp_lt_u32_e64 s[94:95], s91, v150
	v_cmp_lt_u32_e64 s[86:87], s91, v151
	v_cmp_lt_u32_e64 s[0:1], s91, v152
	v_cmp_lt_u32_e64 s[2:3], s91, v153
	v_cndmask_b32_e64 v32, v32, v230, s[94:95]
	v_cndmask_b32_e64 v33, v33, v230, s[86:87]
	v_cndmask_b32_e64 v34, v34, v230, s[0:1]
	v_cndmask_b32_e64 v35, v35, v230, s[2:3]
	v_max3_f32 v184, v0, v1, v2
	v_max3_f32 v184, v184, v3, v4
	v_max3_f32 v184, v184, v5, v6
	v_max3_f32 v184, v184, v7, v8
	v_max3_f32 v184, v184, v9, v10
	v_max3_f32 v184, v184, v11, v12
	v_max3_f32 v184, v184, v13, v14
	v_max3_f32 v184, v184, v15, v16
	v_max3_f32 v184, v184, v17, v18
	v_max3_f32 v184, v184, v19, v20
	v_max3_f32 v184, v184, v21, v22
	v_max3_f32 v184, v184, v23, v24
	v_max3_f32 v184, v184, v25, v26
	v_max3_f32 v184, v184, v27, v28
	v_max3_f32 v184, v184, v29, v30
	v_max3_f32 v184, v184, v31, v32
	v_max3_f32 v184, v184, v33, v34
	v_max_f32_e32 v184, v184, v35
	v_mov_b32_e32 v146, v184
	s_nop 1
	v_permlane16_swap_b32_e32 v184, v146
	s_waitcnt lgkmcnt(0)
	s_add_i32 s93, s76, 0xfffffd00
	s_mov_b32 m0, s12
	v_add_u32_e32 v164, s93, v231
	v_med3_i32 v164, v164, 0, s40
	v_lshl_or_b32 v164, v164, 7, v222
	global_load_lds_dwordx4 v164, s[24:25]
	s_add_i32 m0, s12, 0x400
	v_add_u32_e32 v165, s93, v232
	v_med3_i32 v165, v165, 0, s40
	v_lshl_or_b32 v165, v165, 7, v222
	global_load_lds_dwordx4 v165, s[24:25]
	s_waitcnt vmcnt(8)
	v_add_u32_e32 v154, s13, v223
	v_add_u32_e32 v155, s13, v224
	ds_read_b128 v[202:205], v154
	ds_read_b128 v[206:209], v155
	v_mfma_f32_16x16x32_bf16 v[56:59], v[88:91], v[80:83], 0
	v_mfma_f32_16x16x32_bf16 v[56:59], v[92:95], v[84:87], v[56:59]
	v_max_f32_e32 v184, v184, v146
	v_mov_b32_e32 v146, v184
	s_nop 1
	v_permlane32_swap_b32_e32 v184, v146
	v_max_f32_e32 v184, v184, v146
	v_pk_add_f32 v[0:1], v[0:1], v[184:185] op_sel_hi:[1,0] neg_lo:[0,1] neg_hi:[0,1]
	v_pk_add_f32 v[2:3], v[2:3], v[184:185] op_sel_hi:[1,0] neg_lo:[0,1] neg_hi:[0,1]
	v_pk_add_f32 v[4:5], v[4:5], v[184:185] op_sel_hi:[1,0] neg_lo:[0,1] neg_hi:[0,1]
	v_pk_add_f32 v[6:7], v[6:7], v[184:185] op_sel_hi:[1,0] neg_lo:[0,1] neg_hi:[0,1]
	v_exp_f32_e32 v0, v0
	v_exp_f32_e32 v1, v1
	v_exp_f32_e32 v2, v2
	v_exp_f32_e32 v3, v3
	v_pk_add_f32 v[8:9], v[8:9], v[184:185] op_sel_hi:[1,0] neg_lo:[0,1] neg_hi:[0,1]
	v_pk_add_f32 v[10:11], v[10:11], v[184:185] op_sel_hi:[1,0] neg_lo:[0,1] neg_hi:[0,1]
	v_exp_f32_e32 v4, v4
	v_exp_f32_e32 v5, v5
	v_exp_f32_e32 v6, v6
	v_exp_f32_e32 v7, v7
	v_pk_add_f32 v[12:13], v[12:13], v[184:185] op_sel_hi:[1,0] neg_lo:[0,1] neg_hi:[0,1]
	v_pk_add_f32 v[14:15], v[14:15], v[184:185] op_sel_hi:[1,0] neg_lo:[0,1] neg_hi:[0,1]
	v_exp_f32_e32 v8, v8
	v_exp_f32_e32 v9, v9
	v_exp_f32_e32 v10, v10
	v_exp_f32_e32 v11, v11
	v_pk_add_f32 v[16:17], v[16:17], v[184:185] op_sel_hi:[1,0] neg_lo:[0,1] neg_hi:[0,1]
	v_pk_add_f32 v[18:19], v[18:19], v[184:185] op_sel_hi:[1,0] neg_lo:[0,1] neg_hi:[0,1]
	v_exp_f32_e32 v12, v12
	v_exp_f32_e32 v13, v13
	s_waitcnt lgkmcnt(0)
	s_add_i32 s93, s76, 0xfffffe00
	s_mov_b32 m0, s13
	v_add_u32_e32 v164, s93, v231
	v_med3_i32 v164, v164, 0, s40
	v_lshl_or_b32 v164, v164, 7, v222
	global_load_lds_dwordx4 v164, s[24:25]
	s_add_i32 m0, s13, 0x400
	v_add_u32_e32 v165, s93, v232
	v_med3_i32 v165, v165, 0, s40
	v_lshl_or_b32 v165, v165, 7, v222
	global_load_lds_dwordx4 v165, s[24:25]
	s_waitcnt vmcnt(8)
	v_add_u32_e32 v154, s14, v223
	v_add_u32_e32 v155, s14, v224
	ds_read_b128 v[88:91], v154
	ds_read_b128 v[92:95], v155
	v_mfma_f32_16x16x32_bf16 v[60:63], v[202:205], v[80:83], 0
	v_mfma_f32_16x16x32_bf16 v[60:63], v[206:209], v[84:87], v[60:63]
	v_exp_f32_e32 v14, v14
	v_exp_f32_e32 v15, v15
	v_pk_add_f32 v[20:21], v[20:21], v[184:185] op_sel_hi:[1,0] neg_lo:[0,1] neg_hi:[0,1]
	v_pk_add_f32 v[22:23], v[22:23], v[184:185] op_sel_hi:[1,0] neg_lo:[0,1] neg_hi:[0,1]
	v_exp_f32_e32 v16, v16
	v_exp_f32_e32 v17, v17
	v_exp_f32_e32 v18, v18
	v_exp_f32_e32 v19, v19
	v_pk_add_f32 v[24:25], v[24:25], v[184:185] op_sel_hi:[1,0] neg_lo:[0,1] neg_hi:[0,1]
	v_pk_add_f32 v[26:27], v[26:27], v[184:185] op_sel_hi:[1,0] neg_lo:[0,1] neg_hi:[0,1]
	v_exp_f32_e32 v20, v20
	v_exp_f32_e32 v21, v21
	v_exp_f32_e32 v22, v22
	v_exp_f32_e32 v23, v23
	v_pk_add_f32 v[28:29], v[28:29], v[184:185] op_sel_hi:[1,0] neg_lo:[0,1] neg_hi:[0,1]
	v_pk_add_f32 v[30:31], v[30:31], v[184:185] op_sel_hi:[1,0] neg_lo:[0,1] neg_hi:[0,1]
	v_exp_f32_e32 v24, v24
	v_exp_f32_e32 v25, v25
	v_exp_f32_e32 v26, v26
	v_exp_f32_e32 v27, v27
	v_pk_add_f32 v[32:33], v[32:33], v[184:185] op_sel_hi:[1,0] neg_lo:[0,1] neg_hi:[0,1]
	v_pk_add_f32 v[34:35], v[34:35], v[184:185] op_sel_hi:[1,0] neg_lo:[0,1] neg_hi:[0,1]
	v_exp_f32_e32 v28, v28
	v_exp_f32_e32 v29, v29
	v_exp_f32_e32 v30, v30
	v_exp_f32_e32 v31, v31
	v_exp_f32_e32 v32, v32
	v_exp_f32_e32 v33, v33
	s_waitcnt lgkmcnt(0)
	s_add_i32 s93, s76, 0xffffff00
	s_mov_b32 m0, s14
	v_add_u32_e32 v164, s93, v231
	v_med3_i32 v164, v164, 0, s40
	v_lshl_or_b32 v164, v164, 7, v222
	global_load_lds_dwordx4 v164, s[24:25]
	s_add_i32 m0, s14, 0x400
	v_add_u32_e32 v165, s93, v232
	v_med3_i32 v165, v165, 0, s40
	v_lshl_or_b32 v165, v165, 7, v222
	global_load_lds_dwordx4 v165, s[24:25]
	s_waitcnt vmcnt(8)
	v_add_u32_e32 v154, s15, v223
	v_add_u32_e32 v155, s15, v224
	ds_read_b128 v[202:205], v154
	ds_read_b128 v[206:209], v155
	v_mfma_f32_16x16x32_bf16 v[64:67], v[88:91], v[80:83], 0
	v_mfma_f32_16x16x32_bf16 v[64:67], v[92:95], v[84:87], v[64:67]
	v_exp_f32_e32 v34, v34
	v_exp_f32_e32 v35, v35
	s_nop 0
	v_pk_add_f32 v[146:147], v[0:1], v[2:3]
	v_pk_add_f32 v[148:149], v[4:5], v[6:7]
	v_pk_add_f32 v[146:147], v[146:147], v[8:9]
	v_pk_add_f32 v[148:149], v[148:149], v[10:11]
	v_pk_add_f32 v[146:147], v[146:147], v[12:13]
	v_pk_add_f32 v[148:149], v[148:149], v[14:15]
	v_pk_add_f32 v[146:147], v[146:147], v[16:17]
	v_pk_add_f32 v[148:149], v[148:149], v[18:19]
	v_pk_add_f32 v[146:147], v[146:147], v[20:21]
	v_pk_add_f32 v[148:149], v[148:149], v[22:23]
	v_pk_add_f32 v[146:147], v[146:147], v[24:25]
	v_pk_add_f32 v[148:149], v[148:149], v[26:27]
	v_pk_add_f32 v[146:147], v[146:147], v[28:29]
	v_pk_add_f32 v[148:149], v[148:149], v[30:31]
	v_pk_add_f32 v[146:147], v[146:147], v[32:33]
	v_pk_add_f32 v[148:149], v[148:149], v[34:35]
	s_nop 0
	v_pk_add_f32 v[146:147], v[146:147], v[148:149]
	s_nop 0
	v_add_f32_e32 v185, v146, v147
	v_cvt_pk_bf16_f32 v0, v0, v1
	v_cvt_pk_bf16_f32 v1, v2, v3
	v_cvt_pk_bf16_f32 v4, v4, v5
	v_cvt_pk_bf16_f32 v5, v6, v7
	v_cvt_pk_bf16_f32 v8, v8, v9
	s_waitcnt lgkmcnt(0)
	s_add_i32 s93, s76, 0
	s_mov_b32 m0, s15
	v_add_u32_e32 v164, s93, v231
	v_med3_i32 v164, v164, 0, s40
	v_lshl_or_b32 v164, v164, 7, v222
	global_load_lds_dwordx4 v164, s[24:25]
	s_add_i32 m0, s15, 0x400
	v_add_u32_e32 v165, s93, v232
	v_med3_i32 v165, v165, 0, s40
	v_lshl_or_b32 v165, v165, 7, v222
	global_load_lds_dwordx4 v165, s[24:25]
	s_waitcnt vmcnt(8)
	v_add_u32_e32 v154, s16, v225
	v_add_u32_e32 v155, s16, v226
	v_add_u32_e32 v156, s16, v227
	v_add_u32_e32 v157, s16, v228
	ds_read_b64_tr_b16 v[88:89], v154
	ds_read_b64_tr_b16 v[90:91], v155
	ds_read_b64_tr_b16 v[92:93], v156
	ds_read_b64_tr_b16 v[94:95], v157
	v_mfma_f32_16x16x32_bf16 v[68:71], v[202:205], v[80:83], 0
	v_mfma_f32_16x16x32_bf16 v[68:71], v[206:209], v[84:87], v[68:71]
	v_cvt_pk_bf16_f32 v9, v10, v11
	v_cvt_pk_bf16_f32 v12, v12, v13
	v_cvt_pk_bf16_f32 v13, v14, v15
	v_cvt_pk_bf16_f32 v16, v16, v17
	v_cvt_pk_bf16_f32 v17, v18, v19
	v_cvt_pk_bf16_f32 v20, v20, v21
	v_cvt_pk_bf16_f32 v21, v22, v23
	v_cvt_pk_bf16_f32 v24, v24, v25
	v_cvt_pk_bf16_f32 v25, v26, v27
	v_cvt_pk_bf16_f32 v28, v28, v29
	v_cvt_pk_bf16_f32 v29, v30, v31
	v_cvt_pk_bf16_f32 v32, v32, v33
	v_cvt_pk_bf16_f32 v33, v34, v35
	v_mov_b32_e32 v146, v185
	s_nop 1
	v_permlane16_swap_b32_e32 v185, v146
	v_add_f32_e32 v185, v185, v146
	v_mov_b32_e32 v146, v185
	s_nop 1
	v_permlane32_swap_b32_e32 v185, v146
	v_add_f32_e32 v185, v185, v146
	s_waitcnt lgkmcnt(0)
	s_add_i32 s93, s76, 0x100
	s_mov_b32 m0, s16
	v_add_u32_e32 v164, s93, v231
	v_med3_i32 v164, v164, 0, s40
	v_lshl_or_b32 v164, v164, 7, v222
	global_load_lds_dwordx4 v164, s[24:25]
	s_add_i32 m0, s16, 0x400
	v_add_u32_e32 v165, s93, v232
	v_med3_i32 v165, v165, 0, s40
	v_lshl_or_b32 v165, v165, 7, v222
	global_load_lds_dwordx4 v165, s[24:25]
	s_waitcnt vmcnt(8)
	v_add_u32_e32 v154, s12, v225
	v_add_u32_e32 v155, s12, v226
	v_add_u32_e32 v156, s12, v227
	v_add_u32_e32 v157, s12, v228
	ds_read_b64_tr_b16 v[202:203], v154
	ds_read_b64_tr_b16 v[204:205], v155
	ds_read_b64_tr_b16 v[206:207], v156
	ds_read_b64_tr_b16 v[208:209], v157
	v_mfma_f32_16x16x16_bf16 v[96:99], v[88:89], v[0:1], 0
	v_mfma_f32_16x16x16_bf16 v[100:103], v[90:91], v[0:1], 0
	v_mfma_f32_16x16x16_bf16 v[104:107], v[92:93], v[0:1], 0
	v_mfma_f32_16x16x16_bf16 v[108:111], v[94:95], v[0:1], 0
	v_mov_b32_e32 v189, s85
	v_lshl_add_u32 v189, v216, 4, v189
	v_lshrrev_b32_e32 v146, 4, v189
	v_xor_b32_e32 v146, v146, v189
	v_and_b32_e32 v146, 15, v146
	v_lshlrev_b32_e32 v147, 8, v189
	v_or_b32_e32 v148, 0, v217
	v_xor_b32_e32 v148, v148, v146
	v_lshl_add_u32 v195, v148, 4, v147
	v_or_b32_e32 v148, 4, v217
	v_xor_b32_e32 v148, v148, v146
	v_lshl_add_u32 v196, v148, 4, v147
	v_or_b32_e32 v148, 8, v217
	v_xor_b32_e32 v148, v148, v146
	v_lshl_add_u32 v197, v148, 4, v147
	v_or_b32_e32 v148, 12, v217
	v_xor_b32_e32 v148, v148, v146
	v_lshl_add_u32 v198, v148, 4, v147
	v_lshlrev_b32_e32 v199, 3, v189
	v_add_u32_e32 v199, 0x10000, v199
	ds_read_b64 v[182:183], v199
	ds_read_b128 v[166:169], v195
	ds_read_b128 v[170:173], v196
	ds_read_b128 v[174:177], v197
	ds_read_b128 v[178:181], v198
	s_ashr_i32 s77, s8, 4
	s_sub_i32 s77, 64, s77
	s_sub_i32 s78, s40, s8
	s_ashr_i32 s78, s78, 4
	s_add_i32 s78, s78, 64
	v_cndmask_b32_e64 v36, v36, v230, s[52:53]
	s_waitcnt lgkmcnt(0)
	s_add_i32 s93, s76, 0x200
	s_mov_b32 m0, s12
	v_add_u32_e32 v164, s93, v231
	v_med3_i32 v164, v164, 0, s40
	v_lshl_or_b32 v164, v164, 7, v222
	global_load_lds_dwordx4 v164, s[24:25]
	s_add_i32 m0, s12, 0x400
	v_add_u32_e32 v165, s93, v232
	v_med3_i32 v165, v165, 0, s40
	v_lshl_or_b32 v165, v165, 7, v222
	global_load_lds_dwordx4 v165, s[24:25]
	s_waitcnt vmcnt(8)
	v_add_u32_e32 v154, s13, v225
	v_add_u32_e32 v155, s13, v226
	v_add_u32_e32 v156, s13, v227
	v_add_u32_e32 v157, s13, v228
	ds_read_b64_tr_b16 v[88:89], v154
	ds_read_b64_tr_b16 v[90:91], v155
	ds_read_b64_tr_b16 v[92:93], v156
	ds_read_b64_tr_b16 v[94:95], v157
	v_mfma_f32_16x16x16_bf16 v[96:99], v[202:203], v[4:5], v[96:99]
	v_mfma_f32_16x16x16_bf16 v[100:103], v[204:205], v[4:5], v[100:103]
	v_mfma_f32_16x16x16_bf16 v[104:107], v[206:207], v[4:5], v[104:107]
	v_mfma_f32_16x16x16_bf16 v[108:111], v[208:209], v[4:5], v[108:111]
	v_cndmask_b32_e64 v68, v68, v230, s[62:63]
	v_cndmask_b32_e64 v37, v37, v230, s[56:57]
	v_cndmask_b32_e64 v69, v69, v230, s[64:65]
	v_cndmask_b32_e64 v38, v38, v230, s[58:59]
	v_cndmask_b32_e64 v70, v70, v230, s[70:71]
	v_cndmask_b32_e64 v39, v39, v230, s[60:61]
	v_cndmask_b32_e64 v71, v71, v230, s[72:73]
	v_sub_u32_e32 v200, s77, v229
	s_sub_i32 s91, s78, s77
	v_sub_u32_e32 v150, 0, v200
	v_sub_u32_e32 v151, 1, v200
	v_sub_u32_e32 v152, 2, v200
	v_sub_u32_e32 v153, 3, v200
	v_cmp_lt_u32_e64 s[94:95], s91, v150
	v_cmp_lt_u32_e64 s[86:87], s91, v151
	v_cmp_lt_u32_e64 s[0:1], s91, v152
	v_cmp_lt_u32_e64 s[2:3], s91, v153
	v_cndmask_b32_e64 v36, v36, v230, s[94:95]
	v_cndmask_b32_e64 v37, v37, v230, s[86:87]
	v_cndmask_b32_e64 v38, v38, v230, s[0:1]
	v_cndmask_b32_e64 v39, v39, v230, s[2:3]
	v_sub_u32_e32 v150, 16, v200
	v_sub_u32_e32 v151, 17, v200
	v_sub_u32_e32 v152, 18, v200
	v_sub_u32_e32 v153, 19, v200
	v_cmp_lt_u32_e64 s[94:95], s91, v150
	v_cmp_lt_u32_e64 s[86:87], s91, v151
	v_cmp_lt_u32_e64 s[0:1], s91, v152
	v_cmp_lt_u32_e64 s[2:3], s91, v153
	v_cndmask_b32_e64 v40, v40, v230, s[94:95]
	v_cndmask_b32_e64 v41, v41, v230, s[86:87]
	s_waitcnt lgkmcnt(0)
	s_add_i32 s93, s76, 0x300
	s_mov_b32 m0, s13
	v_add_u32_e32 v164, s93, v231
	v_med3_i32 v164, v164, 0, s40
	v_lshl_or_b32 v164, v164, 7, v222
	global_load_lds_dwordx4 v164, s[24:25]
	s_add_i32 m0, s13, 0x400
	v_add_u32_e32 v165, s93, v232
	v_med3_i32 v165, v165, 0, s40
	v_lshl_or_b32 v165, v165, 7, v222
	global_load_lds_dwordx4 v165, s[24:25]
	s_waitcnt vmcnt(8)
	v_add_u32_e32 v154, s14, v225
	v_add_u32_e32 v155, s14, v226
	v_add_u32_e32 v156, s14, v227
	v_add_u32_e32 v157, s14, v228
	ds_read_b64_tr_b16 v[202:203], v154
	ds_read_b64_tr_b16 v[204:205], v155
	ds_read_b64_tr_b16 v[206:207], v156
	ds_read_b64_tr_b16 v[208:209], v157
	v_mfma_f32_16x16x16_bf16 v[96:99], v[88:89], v[8:9], v[96:99]
	v_mfma_f32_16x16x16_bf16 v[100:103], v[90:91], v[8:9], v[100:103]
	v_mfma_f32_16x16x16_bf16 v[104:107], v[92:93], v[8:9], v[104:107]
	v_mfma_f32_16x16x16_bf16 v[108:111], v[94:95], v[8:9], v[108:111]
	v_cndmask_b32_e64 v42, v42, v230, s[0:1]
	v_cndmask_b32_e64 v43, v43, v230, s[2:3]
	v_sub_u32_e32 v150, 32, v200
	v_sub_u32_e32 v151, 33, v200
	v_sub_u32_e32 v152, 34, v200
	v_sub_u32_e32 v153, 35, v200
	v_cmp_lt_u32_e64 s[94:95], s91, v150
	v_cmp_lt_u32_e64 s[86:87], s91, v151
	v_cmp_lt_u32_e64 s[0:1], s91, v152
	v_cmp_lt_u32_e64 s[2:3], s91, v153
	v_cndmask_b32_e64 v44, v44, v230, s[94:95]
	v_cndmask_b32_e64 v45, v45, v230, s[86:87]
	v_cndmask_b32_e64 v46, v46, v230, s[0:1]
	v_cndmask_b32_e64 v47, v47, v230, s[2:3]
	v_sub_u32_e32 v150, 48, v200
	v_sub_u32_e32 v151, 49, v200
	v_sub_u32_e32 v152, 50, v200
	v_sub_u32_e32 v153, 51, v200
	v_cmp_lt_u32_e64 s[94:95], s91, v150
	v_cmp_lt_u32_e64 s[86:87], s91, v151
	v_cmp_lt_u32_e64 s[0:1], s91, v152
	v_cmp_lt_u32_e64 s[2:3], s91, v153
	v_cndmask_b32_e64 v48, v48, v230, s[94:95]
	v_cndmask_b32_e64 v49, v49, v230, s[86:87]
	v_cndmask_b32_e64 v50, v50, v230, s[0:1]
	v_cndmask_b32_e64 v51, v51, v230, s[2:3]
	v_sub_u32_e32 v150, 64, v200
	v_sub_u32_e32 v151, 0x41, v200
	v_sub_u32_e32 v152, 0x42, v200
	v_sub_u32_e32 v153, 0x43, v200
	v_cmp_lt_u32_e64 s[94:95], s91, v150
	s_waitcnt lgkmcnt(0)
	s_add_i32 s93, s76, 0x400
	s_mov_b32 m0, s14
	v_add_u32_e32 v164, s93, v231
	v_med3_i32 v164, v164, 0, s40
	v_lshl_or_b32 v164, v164, 7, v222
	global_load_lds_dwordx4 v164, s[24:25]
	s_add_i32 m0, s14, 0x400
	v_add_u32_e32 v165, s93, v232
	v_med3_i32 v165, v165, 0, s40
	v_lshl_or_b32 v165, v165, 7, v222
	global_load_lds_dwordx4 v165, s[24:25]
	s_waitcnt vmcnt(8)
	v_add_u32_e32 v154, s15, v225
	v_add_u32_e32 v155, s15, v226
	v_add_u32_e32 v156, s15, v227
	v_add_u32_e32 v157, s15, v228
	ds_read_b64_tr_b16 v[88:89], v154
	ds_read_b64_tr_b16 v[90:91], v155
	ds_read_b64_tr_b16 v[92:93], v156
	ds_read_b64_tr_b16 v[94:95], v157
	v_mfma_f32_16x16x16_bf16 v[96:99], v[202:203], v[12:13], v[96:99]
	v_mfma_f32_16x16x16_bf16 v[100:103], v[204:205], v[12:13], v[100:103]
	v_mfma_f32_16x16x16_bf16 v[104:107], v[206:207], v[12:13], v[104:107]
	v_mfma_f32_16x16x16_bf16 v[108:111], v[208:209], v[12:13], v[108:111]
	v_cmp_lt_u32_e64 s[86:87], s91, v151
	v_cmp_lt_u32_e64 s[0:1], s91, v152
	v_cmp_lt_u32_e64 s[2:3], s91, v153
	v_cndmask_b32_e64 v52, v52, v230, s[94:95]
	v_cndmask_b32_e64 v53, v53, v230, s[86:87]
	v_cndmask_b32_e64 v54, v54, v230, s[0:1]
	v_cndmask_b32_e64 v55, v55, v230, s[2:3]
	v_sub_u32_e32 v150, 0x50, v200
	v_sub_u32_e32 v151, 0x51, v200
	v_sub_u32_e32 v152, 0x52, v200
	v_sub_u32_e32 v153, 0x53, v200
	v_cmp_lt_u32_e64 s[94:95], s91, v150
	v_cmp_lt_u32_e64 s[86:87], s91, v151
	v_cmp_lt_u32_e64 s[0:1], s91, v152
	v_cmp_lt_u32_e64 s[2:3], s91, v153
	v_cndmask_b32_e64 v56, v56, v230, s[94:95]
	v_cndmask_b32_e64 v57, v57, v230, s[86:87]
	v_cndmask_b32_e64 v58, v58, v230, s[0:1]
	v_cndmask_b32_e64 v59, v59, v230, s[2:3]
	v_sub_u32_e32 v150, 0x60, v200
	v_sub_u32_e32 v151, 0x61, v200
	v_sub_u32_e32 v152, 0x62, v200
	v_sub_u32_e32 v153, 0x63, v200
	v_cmp_lt_u32_e64 s[94:95], s91, v150
	v_cmp_lt_u32_e64 s[86:87], s91, v151
	v_cmp_lt_u32_e64 s[0:1], s91, v152
	v_cmp_lt_u32_e64 s[2:3], s91, v153
	v_cndmask_b32_e64 v60, v60, v230, s[94:95]
	v_cndmask_b32_e64 v61, v61, v230, s[86:87]
	v_cndmask_b32_e64 v62, v62, v230, s[0:1]
	v_cndmask_b32_e64 v63, v63, v230, s[2:3]
	s_waitcnt lgkmcnt(0)
	s_add_i32 s93, s8, 0xfffffc00
	s_mov_b32 m0, s15
	v_add_u32_e32 v164, s93, v231
	v_med3_i32 v164, v164, 0, s40
	v_lshl_or_b32 v164, v164, 7, v222
	global_load_lds_dwordx4 v164, s[24:25]
	s_add_i32 m0, s15, 0x400
	v_add_u32_e32 v165, s93, v232
	v_med3_i32 v165, v165, 0, s40
	v_lshl_or_b32 v165, v165, 7, v222
	global_load_lds_dwordx4 v165, s[24:25]
	s_waitcnt vmcnt(8)
	v_add_u32_e32 v154, s16, v225
	v_add_u32_e32 v155, s16, v226
	v_add_u32_e32 v156, s16, v227
	v_add_u32_e32 v157, s16, v228
	ds_read_b64_tr_b16 v[202:203], v154
	ds_read_b64_tr_b16 v[204:205], v155
	ds_read_b64_tr_b16 v[206:207], v156
	ds_read_b64_tr_b16 v[208:209], v157
	v_mfma_f32_16x16x16_bf16 v[96:99], v[88:89], v[16:17], v[96:99]
	v_mfma_f32_16x16x16_bf16 v[100:103], v[90:91], v[16:17], v[100:103]
	v_mfma_f32_16x16x16_bf16 v[104:107], v[92:93], v[16:17], v[104:107]
	v_mfma_f32_16x16x16_bf16 v[108:111], v[94:95], v[16:17], v[108:111]
	v_sub_u32_e32 v150, 0x70, v200
	v_sub_u32_e32 v151, 0x71, v200
	v_sub_u32_e32 v152, 0x72, v200
	v_sub_u32_e32 v153, 0x73, v200
	v_cmp_lt_u32_e64 s[94:95], s91, v150
	v_cmp_lt_u32_e64 s[86:87], s91, v151
	v_cmp_lt_u32_e64 s[0:1], s91, v152
	v_cmp_lt_u32_e64 s[2:3], s91, v153
	v_cndmask_b32_e64 v64, v64, v230, s[94:95]
	v_cndmask_b32_e64 v65, v65, v230, s[86:87]
	v_cndmask_b32_e64 v66, v66, v230, s[0:1]
	v_cndmask_b32_e64 v67, v67, v230, s[2:3]
	v_sub_u32_e32 v150, 0x80, v200
	v_sub_u32_e32 v151, 0x81, v200
	v_sub_u32_e32 v152, 0x82, v200
	v_sub_u32_e32 v153, 0x83, v200
	v_cmp_lt_u32_e64 s[94:95], s91, v150
	v_cmp_lt_u32_e64 s[86:87], s91, v151
	v_cmp_lt_u32_e64 s[0:1], s91, v152
	v_cmp_lt_u32_e64 s[2:3], s91, v153
	v_cndmask_b32_e64 v68, v68, v230, s[94:95]
	v_cndmask_b32_e64 v69, v69, v230, s[86:87]
	v_cndmask_b32_e64 v70, v70, v230, s[0:1]
	v_cndmask_b32_e64 v71, v71, v230, s[2:3]
	v_max3_f32 v186, v36, v37, v38
	v_max3_f32 v186, v186, v39, v40
	v_max3_f32 v186, v186, v41, v42
	v_max3_f32 v186, v186, v43, v44
	v_max3_f32 v186, v186, v45, v46
	v_max3_f32 v186, v186, v47, v48
	v_max3_f32 v186, v186, v49, v50
	s_waitcnt lgkmcnt(0)
	s_add_i32 s93, s8, 0xfffffd00
	s_mov_b32 m0, s16
	v_add_u32_e32 v164, s93, v231
	v_med3_i32 v164, v164, 0, s40
	v_lshl_or_b32 v164, v164, 7, v222
	global_load_lds_dwordx4 v164, s[24:25]
	s_add_i32 m0, s16, 0x400
	v_add_u32_e32 v165, s93, v232
	v_med3_i32 v165, v165, 0, s40
	v_lshl_or_b32 v165, v165, 7, v222
	global_load_lds_dwordx4 v165, s[24:25]
	s_waitcnt vmcnt(8)
	v_add_u32_e32 v154, s12, v225
	v_add_u32_e32 v155, s12, v226
	v_add_u32_e32 v156, s12, v227
	v_add_u32_e32 v157, s12, v228
	ds_read_b64_tr_b16 v[88:89], v154
	ds_read_b64_tr_b16 v[90:91], v155
	ds_read_b64_tr_b16 v[92:93], v156
	ds_read_b64_tr_b16 v[94:95], v157
	v_mfma_f32_16x16x16_bf16 v[96:99], v[202:203], v[20:21], v[96:99]
	v_mfma_f32_16x16x16_bf16 v[100:103], v[204:205], v[20:21], v[100:103]
	v_mfma_f32_16x16x16_bf16 v[104:107], v[206:207], v[20:21], v[104:107]
	v_mfma_f32_16x16x16_bf16 v[108:111], v[208:209], v[20:21], v[108:111]
	v_max3_f32 v186, v186, v51, v52
	v_max3_f32 v186, v186, v53, v54
	v_max3_f32 v186, v186, v55, v56
	v_max3_f32 v186, v186, v57, v58
	v_max3_f32 v186, v186, v59, v60
	v_max3_f32 v186, v186, v61, v62
	v_max3_f32 v186, v186, v63, v64
	v_max3_f32 v186, v186, v65, v66
	v_max3_f32 v186, v186, v67, v68
	v_max3_f32 v186, v186, v69, v70
	v_max_f32_e32 v186, v186, v71
	v_mov_b32_e32 v146, v186
	s_nop 1
	v_permlane16_swap_b32_e32 v186, v146
	v_max_f32_e32 v186, v186, v146
	v_mov_b32_e32 v146, v186
	s_nop 1
	v_permlane32_swap_b32_e32 v186, v146
	v_max_f32_e32 v186, v186, v146
	v_pk_add_f32 v[36:37], v[36:37], v[186:187] op_sel_hi:[1,0] neg_lo:[0,1] neg_hi:[0,1]
	v_pk_add_f32 v[38:39], v[38:39], v[186:187] op_sel_hi:[1,0] neg_lo:[0,1] neg_hi:[0,1]
	v_pk_add_f32 v[40:41], v[40:41], v[186:187] op_sel_hi:[1,0] neg_lo:[0,1] neg_hi:[0,1]
	v_pk_add_f32 v[42:43], v[42:43], v[186:187] op_sel_hi:[1,0] neg_lo:[0,1] neg_hi:[0,1]
	v_exp_f32_e32 v36, v36
	v_exp_f32_e32 v37, v37
	v_exp_f32_e32 v38, v38
	v_exp_f32_e32 v39, v39
	v_pk_add_f32 v[44:45], v[44:45], v[186:187] op_sel_hi:[1,0] neg_lo:[0,1] neg_hi:[0,1]
	v_pk_add_f32 v[46:47], v[46:47], v[186:187] op_sel_hi:[1,0] neg_lo:[0,1] neg_hi:[0,1]
	v_exp_f32_e32 v40, v40
	v_exp_f32_e32 v41, v41
	v_exp_f32_e32 v42, v42
	v_exp_f32_e32 v43, v43
	s_waitcnt lgkmcnt(0)
	s_add_i32 s93, s8, 0xfffffe00
	s_mov_b32 m0, s12
	v_add_u32_e32 v164, s93, v231
	v_med3_i32 v164, v164, 0, s40
	v_lshl_or_b32 v164, v164, 7, v222
	global_load_lds_dwordx4 v164, s[24:25]
	s_add_i32 m0, s12, 0x400
	v_add_u32_e32 v165, s93, v232
	v_med3_i32 v165, v165, 0, s40
	v_lshl_or_b32 v165, v165, 7, v222
	global_load_lds_dwordx4 v165, s[24:25]
	s_waitcnt vmcnt(8)
	v_add_u32_e32 v154, s13, v225
	v_add_u32_e32 v155, s13, v226
	v_add_u32_e32 v156, s13, v227
	v_add_u32_e32 v157, s13, v228
	ds_read_b64_tr_b16 v[202:203], v154
	ds_read_b64_tr_b16 v[204:205], v155
	ds_read_b64_tr_b16 v[206:207], v156
	ds_read_b64_tr_b16 v[208:209], v157
	v_mfma_f32_16x16x16_bf16 v[96:99], v[88:89], v[24:25], v[96:99]
	v_mfma_f32_16x16x16_bf16 v[100:103], v[90:91], v[24:25], v[100:103]
	v_mfma_f32_16x16x16_bf16 v[104:107], v[92:93], v[24:25], v[104:107]
	v_mfma_f32_16x16x16_bf16 v[108:111], v[94:95], v[24:25], v[108:111]
	v_pk_add_f32 v[48:49], v[48:49], v[186:187] op_sel_hi:[1,0] neg_lo:[0,1] neg_hi:[0,1]
	v_pk_add_f32 v[50:51], v[50:51], v[186:187] op_sel_hi:[1,0] neg_lo:[0,1] neg_hi:[0,1]
	v_exp_f32_e32 v44, v44
	v_exp_f32_e32 v45, v45
	v_exp_f32_e32 v46, v46
	v_exp_f32_e32 v47, v47
	v_pk_add_f32 v[52:53], v[52:53], v[186:187] op_sel_hi:[1,0] neg_lo:[0,1] neg_hi:[0,1]
	v_pk_add_f32 v[54:55], v[54:55], v[186:187] op_sel_hi:[1,0] neg_lo:[0,1] neg_hi:[0,1]
	v_exp_f32_e32 v48, v48
	v_exp_f32_e32 v49, v49
	v_exp_f32_e32 v50, v50
	v_exp_f32_e32 v51, v51
	v_pk_add_f32 v[56:57], v[56:57], v[186:187] op_sel_hi:[1,0] neg_lo:[0,1] neg_hi:[0,1]
	v_pk_add_f32 v[58:59], v[58:59], v[186:187] op_sel_hi:[1,0] neg_lo:[0,1] neg_hi:[0,1]
	v_exp_f32_e32 v52, v52
	v_exp_f32_e32 v53, v53
	v_exp_f32_e32 v54, v54
	v_exp_f32_e32 v55, v55
	v_pk_add_f32 v[60:61], v[60:61], v[186:187] op_sel_hi:[1,0] neg_lo:[0,1] neg_hi:[0,1]
	v_pk_add_f32 v[62:63], v[62:63], v[186:187] op_sel_hi:[1,0] neg_lo:[0,1] neg_hi:[0,1]
	v_exp_f32_e32 v56, v56
	v_exp_f32_e32 v57, v57
	v_exp_f32_e32 v58, v58
	v_exp_f32_e32 v59, v59
	v_pk_add_f32 v[64:65], v[64:65], v[186:187] op_sel_hi:[1,0] neg_lo:[0,1] neg_hi:[0,1]
	v_pk_add_f32 v[66:67], v[66:67], v[186:187] op_sel_hi:[1,0] neg_lo:[0,1] neg_hi:[0,1]
	v_exp_f32_e32 v60, v60
	v_exp_f32_e32 v61, v61
	v_exp_f32_e32 v62, v62
	v_exp_f32_e32 v63, v63
	v_pk_add_f32 v[68:69], v[68:69], v[186:187] op_sel_hi:[1,0] neg_lo:[0,1] neg_hi:[0,1]
	s_waitcnt lgkmcnt(0)
	s_add_i32 s93, s8, 0xffffff00
	s_mov_b32 m0, s13
	v_add_u32_e32 v164, s93, v231
	v_med3_i32 v164, v164, 0, s40
	v_lshl_or_b32 v164, v164, 7, v222
	global_load_lds_dwordx4 v164, s[24:25]
	s_add_i32 m0, s13, 0x400
	v_add_u32_e32 v165, s93, v232
	v_med3_i32 v165, v165, 0, s40
	v_lshl_or_b32 v165, v165, 7, v222
	global_load_lds_dwordx4 v165, s[24:25]
	s_waitcnt vmcnt(8)
	v_add_u32_e32 v154, s14, v225
	v_add_u32_e32 v155, s14, v226
	v_add_u32_e32 v156, s14, v227
	v_add_u32_e32 v157, s14, v228
	ds_read_b64_tr_b16 v[88:89], v154
	ds_read_b64_tr_b16 v[90:91], v155
	ds_read_b64_tr_b16 v[92:93], v156
	ds_read_b64_tr_b16 v[94:95], v157
	v_mfma_f32_16x16x16_bf16 v[96:99], v[202:203], v[28:29], v[96:99]
	v_mfma_f32_16x16x16_bf16 v[100:103], v[204:205], v[28:29], v[100:103]
	v_mfma_f32_16x16x16_bf16 v[104:107], v[206:207], v[28:29], v[104:107]
	v_mfma_f32_16x16x16_bf16 v[108:111], v[208:209], v[28:29], v[108:111]
	v_pk_add_f32 v[70:71], v[70:71], v[186:187] op_sel_hi:[1,0] neg_lo:[0,1] neg_hi:[0,1]
	v_exp_f32_e32 v64, v64
	v_exp_f32_e32 v65, v65
	v_exp_f32_e32 v66, v66
	v_exp_f32_e32 v67, v67
	v_exp_f32_e32 v68, v68
	v_exp_f32_e32 v69, v69
	v_exp_f32_e32 v70, v70
	v_exp_f32_e32 v71, v71
	s_nop 0
	v_pk_add_f32 v[146:147], v[36:37], v[38:39]
	v_pk_add_f32 v[148:149], v[40:41], v[42:43]
	v_pk_add_f32 v[146:147], v[146:147], v[44:45]
	v_pk_add_f32 v[148:149], v[148:149], v[46:47]
	v_pk_add_f32 v[146:147], v[146:147], v[48:49]
	v_pk_add_f32 v[148:149], v[148:149], v[50:51]
	v_pk_add_f32 v[146:147], v[146:147], v[52:53]
	v_pk_add_f32 v[148:149], v[148:149], v[54:55]
	v_pk_add_f32 v[146:147], v[146:147], v[56:57]
	v_pk_add_f32 v[148:149], v[148:149], v[58:59]
	v_pk_add_f32 v[146:147], v[146:147], v[60:61]
	v_pk_add_f32 v[148:149], v[148:149], v[62:63]
	v_pk_add_f32 v[146:147], v[146:147], v[64:65]
	v_pk_add_f32 v[148:149], v[148:149], v[66:67]
	v_pk_add_f32 v[146:147], v[146:147], v[68:69]
	v_pk_add_f32 v[148:149], v[148:149], v[70:71]
	s_nop 0
	v_pk_add_f32 v[146:147], v[146:147], v[148:149]
	s_nop 0
	v_add_f32_e32 v187, v146, v147
	v_cvt_pk_bf16_f32 v36, v36, v37
	s_waitcnt lgkmcnt(0)
	s_add_i32 s93, s8, 0
	s_mov_b32 m0, s14
	v_add_u32_e32 v164, s93, v231
	v_med3_i32 v164, v164, 0, s40
	v_lshl_or_b32 v164, v164, 7, v222
	global_load_lds_dwordx4 v164, s[24:25]
	s_add_i32 m0, s14, 0x400
	v_add_u32_e32 v165, s93, v232
	v_med3_i32 v165, v165, 0, s40
	v_lshl_or_b32 v165, v165, 7, v222
	global_load_lds_dwordx4 v165, s[24:25]
	s_waitcnt vmcnt(8)
	v_add_u32_e32 v72, s15, v225
	v_add_u32_e32 v73, s15, v226
	v_add_u32_e32 v74, s15, v227
	v_add_u32_e32 v75, s15, v228
	ds_read_b64_tr_b16 v[202:203], v72
	ds_read_b64_tr_b16 v[204:205], v73
	ds_read_b64_tr_b16 v[206:207], v74
	ds_read_b64_tr_b16 v[208:209], v75
	v_mfma_f32_16x16x16_bf16 v[96:99], v[88:89], v[32:33], v[96:99]
	v_mfma_f32_16x16x16_bf16 v[100:103], v[90:91], v[32:33], v[100:103]
	v_mfma_f32_16x16x16_bf16 v[104:107], v[92:93], v[32:33], v[104:107]
	v_mfma_f32_16x16x16_bf16 v[108:111], v[94:95], v[32:33], v[108:111]
	v_cvt_pk_bf16_f32 v37, v38, v39
	v_cvt_pk_bf16_f32 v40, v40, v41
	v_cvt_pk_bf16_f32 v41, v42, v43
	v_cvt_pk_bf16_f32 v44, v44, v45
	v_cvt_pk_bf16_f32 v45, v46, v47
	v_cvt_pk_bf16_f32 v48, v48, v49
	v_cvt_pk_bf16_f32 v49, v50, v51
	v_cvt_pk_bf16_f32 v52, v52, v53
	v_cvt_pk_bf16_f32 v53, v54, v55
	v_cvt_pk_bf16_f32 v56, v56, v57
	v_cvt_pk_bf16_f32 v57, v58, v59
	v_cvt_pk_bf16_f32 v60, v60, v61
	v_cvt_pk_bf16_f32 v61, v62, v63
	v_cvt_pk_bf16_f32 v64, v64, v65
	v_cvt_pk_bf16_f32 v65, v66, v67
	v_cvt_pk_bf16_f32 v68, v68, v69
	v_cvt_pk_bf16_f32 v69, v70, v71
	v_mov_b32_e32 v146, v187
	s_nop 1
	v_permlane16_swap_b32_e32 v187, v146
	v_add_f32_e32 v187, v187, v146
	v_mov_b32_e32 v146, v187
	s_nop 1
	v_permlane32_swap_b32_e32 v187, v146
	v_add_f32_e32 v187, v187, v146
	s_waitcnt lgkmcnt(0)
	s_add_i32 s93, s8, 0x100
	s_mov_b32 m0, s15
	v_add_u32_e32 v164, s93, v231
	v_med3_i32 v164, v164, 0, s40
	v_lshl_or_b32 v164, v164, 7, v222
	global_load_lds_dwordx4 v164, s[24:25]
	s_add_i32 m0, s15, 0x400
	v_add_u32_e32 v165, s93, v232
	v_med3_i32 v165, v165, 0, s40
	v_lshl_or_b32 v165, v165, 7, v222
	global_load_lds_dwordx4 v165, s[24:25]
	s_waitcnt vmcnt(8)
	v_add_u32_e32 v72, s16, v225
	v_add_u32_e32 v73, s16, v226
	v_add_u32_e32 v74, s16, v227
	v_add_u32_e32 v75, s16, v228
	ds_read_b64_tr_b16 v[88:89], v72
	ds_read_b64_tr_b16 v[90:91], v73
	ds_read_b64_tr_b16 v[92:93], v74
	ds_read_b64_tr_b16 v[94:95], v75
	v_mfma_f32_16x16x16_bf16 v[112:115], v[202:203], v[36:37], 0
	v_mfma_f32_16x16x16_bf16 v[116:119], v[204:205], v[36:37], 0
	v_mfma_f32_16x16x16_bf16 v[120:123], v[206:207], v[36:37], 0
	v_mfma_f32_16x16x16_bf16 v[124:127], v[208:209], v[36:37], 0
	s_waitcnt lgkmcnt(0)
	v_max_f32_e32 v146, v144, v184
	v_sub_f32_e32 v148, v144, v146
	v_sub_f32_e32 v150, v184, v146
	v_exp_f32_e32 v148, v148
	v_exp_f32_e32 v150, v150
	v_mov_b32_e32 v184, v146
	v_mul_f32_e32 v185, v185, v150
	v_fmac_f32_e32 v185, v145, v148
	v_pk_mul_f32 v[96:97], v[150:151], v[96:97] op_sel_hi:[0,1]
	v_pk_mul_f32 v[98:99], v[150:151], v[98:99] op_sel_hi:[0,1]
	v_pk_mul_f32 v[100:101], v[150:151], v[100:101] op_sel_hi:[0,1]
	s_waitcnt lgkmcnt(0)
	s_add_i32 s93, s8, 0x200
	s_mov_b32 m0, s16
	v_add_u32_e32 v164, s93, v231
	v_med3_i32 v164, v164, 0, s40
	v_lshl_or_b32 v164, v164, 7, v222
	global_load_lds_dwordx4 v164, s[24:25]
	s_add_i32 m0, s16, 0x400
	v_add_u32_e32 v165, s93, v232
	v_med3_i32 v165, v165, 0, s40
	v_lshl_or_b32 v165, v165, 7, v222
	global_load_lds_dwordx4 v165, s[24:25]
	s_waitcnt vmcnt(8)
	v_add_u32_e32 v72, s12, v225
	v_add_u32_e32 v73, s12, v226
	v_add_u32_e32 v74, s12, v227
	v_add_u32_e32 v75, s12, v228
	ds_read_b64_tr_b16 v[202:203], v72
	ds_read_b64_tr_b16 v[204:205], v73
	ds_read_b64_tr_b16 v[206:207], v74
	ds_read_b64_tr_b16 v[208:209], v75
	v_mfma_f32_16x16x16_bf16 v[112:115], v[88:89], v[40:41], v[112:115]
	v_mfma_f32_16x16x16_bf16 v[116:119], v[90:91], v[40:41], v[116:119]
	v_mfma_f32_16x16x16_bf16 v[120:123], v[92:93], v[40:41], v[120:123]
	v_mfma_f32_16x16x16_bf16 v[124:127], v[94:95], v[40:41], v[124:127]
	v_pk_mul_f32 v[102:103], v[150:151], v[102:103] op_sel_hi:[0,1]
	v_pk_mul_f32 v[104:105], v[150:151], v[104:105] op_sel_hi:[0,1]
	v_pk_mul_f32 v[106:107], v[150:151], v[106:107] op_sel_hi:[0,1]
	v_pk_mul_f32 v[108:109], v[150:151], v[108:109] op_sel_hi:[0,1]
	v_pk_mul_f32 v[110:111], v[150:151], v[110:111] op_sel_hi:[0,1]
	v_pk_fma_f32 v[96:97], v[148:149], v[128:129], v[96:97] op_sel_hi:[0,1,1]
	v_pk_fma_f32 v[98:99], v[148:149], v[130:131], v[98:99] op_sel_hi:[0,1,1]
	v_pk_fma_f32 v[100:101], v[148:149], v[132:133], v[100:101] op_sel_hi:[0,1,1]
	v_pk_fma_f32 v[102:103], v[148:149], v[134:135], v[102:103] op_sel_hi:[0,1,1]
	v_pk_fma_f32 v[104:105], v[148:149], v[136:137], v[104:105] op_sel_hi:[0,1,1]
	v_pk_fma_f32 v[106:107], v[148:149], v[138:139], v[106:107] op_sel_hi:[0,1,1]
	v_pk_fma_f32 v[108:109], v[148:149], v[140:141], v[108:109] op_sel_hi:[0,1,1]
	s_waitcnt lgkmcnt(0)
	s_add_i32 s93, s8, 0x300
	s_mov_b32 m0, s12
	v_add_u32_e32 v164, s93, v231
	v_med3_i32 v164, v164, 0, s40
	v_lshl_or_b32 v164, v164, 7, v222
	global_load_lds_dwordx4 v164, s[24:25]
	s_add_i32 m0, s12, 0x400
	v_add_u32_e32 v165, s93, v232
	v_med3_i32 v165, v165, 0, s40
	v_lshl_or_b32 v165, v165, 7, v222
	global_load_lds_dwordx4 v165, s[24:25]
	s_waitcnt vmcnt(8)
	v_add_u32_e32 v72, s13, v225
	v_add_u32_e32 v73, s13, v226
	v_add_u32_e32 v74, s13, v227
	v_add_u32_e32 v75, s13, v228
	ds_read_b64_tr_b16 v[88:89], v72
	ds_read_b64_tr_b16 v[90:91], v73
	ds_read_b64_tr_b16 v[92:93], v74
	ds_read_b64_tr_b16 v[94:95], v75
	v_mfma_f32_16x16x16_bf16 v[112:115], v[202:203], v[44:45], v[112:115]
	v_mfma_f32_16x16x16_bf16 v[116:119], v[204:205], v[44:45], v[116:119]
	v_mfma_f32_16x16x16_bf16 v[120:123], v[206:207], v[44:45], v[120:123]
	v_mfma_f32_16x16x16_bf16 v[124:127], v[208:209], v[44:45], v[124:127]
	v_pk_fma_f32 v[110:111], v[148:149], v[142:143], v[110:111] op_sel_hi:[0,1,1]
	v_div_scale_f32 v147, s[94:95], v185, v185, 1.0
	v_rcp_f32_e32 v148, v147
	v_div_scale_f32 v149, vcc, 1.0, v185, 1.0
	v_fma_f32 v150, -v147, v148, 1.0
	v_fmac_f32_e32 v148, v150, v148
	v_mul_f32_e32 v150, v149, v148
	v_fma_f32 v151, -v147, v150, v149
	v_fmac_f32_e32 v150, v151, v148
	v_fma_f32 v147, -v147, v150, v149
	s_nop 1
	v_div_fmas_f32 v147, v147, v148, v150
	s_waitcnt lgkmcnt(0)
	s_add_i32 s93, s8, 0x400
	s_mov_b32 m0, s13
	v_add_u32_e32 v164, s93, v231
	v_med3_i32 v164, v164, 0, s40
	v_lshl_or_b32 v164, v164, 7, v222
	global_load_lds_dwordx4 v164, s[24:25]
	s_add_i32 m0, s13, 0x400
	v_add_u32_e32 v165, s93, v232
	v_med3_i32 v165, v165, 0, s40
	v_lshl_or_b32 v165, v165, 7, v222
	global_load_lds_dwordx4 v165, s[24:25]
	s_waitcnt vmcnt(8)
	v_add_u32_e32 v72, s14, v225
	v_add_u32_e32 v73, s14, v226
	v_add_u32_e32 v74, s14, v227
	v_add_u32_e32 v75, s14, v228
	ds_read_b64_tr_b16 v[202:203], v72
	ds_read_b64_tr_b16 v[204:205], v73
	ds_read_b64_tr_b16 v[206:207], v74
	ds_read_b64_tr_b16 v[208:209], v75
	v_mfma_f32_16x16x16_bf16 v[112:115], v[88:89], v[48:49], v[112:115]
	v_mfma_f32_16x16x16_bf16 v[116:119], v[90:91], v[48:49], v[116:119]
	v_mfma_f32_16x16x16_bf16 v[120:123], v[92:93], v[48:49], v[120:123]
	v_mfma_f32_16x16x16_bf16 v[124:127], v[94:95], v[48:49], v[124:127]
	v_div_fixup_f32 v152, v147, v185, 1.0
	v_pk_mul_f32 v[96:97], v[152:153], v[96:97] op_sel_hi:[0,1]
	v_pk_mul_f32 v[98:99], v[152:153], v[98:99] op_sel_hi:[0,1]
	v_pk_mul_f32 v[100:101], v[152:153], v[100:101] op_sel_hi:[0,1]
	v_pk_mul_f32 v[102:103], v[152:153], v[102:103] op_sel_hi:[0,1]
	v_pk_mul_f32 v[104:105], v[152:153], v[104:105] op_sel_hi:[0,1]
	v_pk_mul_f32 v[106:107], v[152:153], v[106:107] op_sel_hi:[0,1]
	v_pk_mul_f32 v[108:109], v[152:153], v[108:109] op_sel_hi:[0,1]
	v_pk_mul_f32 v[110:111], v[152:153], v[110:111] op_sel_hi:[0,1]
	v_mul_f32_e32 v155, v97, v97
	v_mul_f32_e32 v156, v99, v99
	v_fmac_f32_e32 v155, v96, v96
	s_waitcnt lgkmcnt(0)
	s_add_i32 s93, s79, 0
	s_mov_b32 m0, s14
	v_add_u32_e32 v164, s93, v162
	v_lshl_or_b32 v164, v164, 7, v220
	global_load_lds_dwordx4 v164, s[30:31]
	s_add_i32 m0, s14, 0x400
	v_add_u32_e32 v165, s93, v163
	v_lshl_or_b32 v165, v165, 7, v221
	global_load_lds_dwordx4 v165, s[30:31]
	s_waitcnt vmcnt(8)
	v_add_u32_e32 v72, s15, v225
	v_add_u32_e32 v73, s15, v226
	v_add_u32_e32 v74, s15, v227
	v_add_u32_e32 v75, s15, v228
	ds_read_b64_tr_b16 v[88:89], v72
	ds_read_b64_tr_b16 v[90:91], v73
	ds_read_b64_tr_b16 v[92:93], v74
	ds_read_b64_tr_b16 v[94:95], v75
	v_mfma_f32_16x16x16_bf16 v[112:115], v[202:203], v[52:53], v[112:115]
	v_mfma_f32_16x16x16_bf16 v[116:119], v[204:205], v[52:53], v[116:119]
	v_mfma_f32_16x16x16_bf16 v[120:123], v[206:207], v[52:53], v[120:123]
	v_mfma_f32_16x16x16_bf16 v[124:127], v[208:209], v[52:53], v[124:127]
	v_fmac_f32_e32 v156, v98, v98
	v_add_f32_e32 v154, v155, v156
	v_mul_f32_e32 v155, v101, v101
	v_mul_f32_e32 v156, v103, v103
	v_fmac_f32_e32 v155, v100, v100
	v_fmac_f32_e32 v156, v102, v102
	v_add_f32_e32 v155, v155, v156
	v_add_f32_e32 v154, v154, v155
	v_mul_f32_e32 v155, v105, v105
	v_mul_f32_e32 v156, v107, v107
	v_fmac_f32_e32 v155, v104, v104
	v_fmac_f32_e32 v156, v106, v106
	s_waitcnt lgkmcnt(0)
	s_add_i32 s93, s79, 16
	s_mov_b32 m0, s15
	v_add_u32_e32 v164, s93, v162
	v_lshl_or_b32 v164, v164, 7, v220
	global_load_lds_dwordx4 v164, s[30:31]
	s_add_i32 m0, s15, 0x400
	v_add_u32_e32 v165, s93, v163
	v_lshl_or_b32 v165, v165, 7, v221
	global_load_lds_dwordx4 v165, s[30:31]
	s_waitcnt vmcnt(8)
	v_add_u32_e32 v72, s16, v225
	v_add_u32_e32 v73, s16, v226
	v_add_u32_e32 v74, s16, v227
	v_add_u32_e32 v75, s16, v228
	ds_read_b64_tr_b16 v[202:203], v72
	ds_read_b64_tr_b16 v[204:205], v73
	ds_read_b64_tr_b16 v[206:207], v74
	ds_read_b64_tr_b16 v[208:209], v75
	v_mfma_f32_16x16x16_bf16 v[112:115], v[88:89], v[56:57], v[112:115]
	v_mfma_f32_16x16x16_bf16 v[116:119], v[90:91], v[56:57], v[116:119]
	v_mfma_f32_16x16x16_bf16 v[120:123], v[92:93], v[56:57], v[120:123]
	v_mfma_f32_16x16x16_bf16 v[124:127], v[94:95], v[56:57], v[124:127]
	v_add_f32_e32 v155, v155, v156
	v_add_f32_e32 v154, v154, v155
	v_mul_f32_e32 v155, v109, v109
	v_mul_f32_e32 v156, v111, v111
	v_fmac_f32_e32 v155, v108, v108
	v_fmac_f32_e32 v156, v110, v110
	v_add_f32_e32 v155, v155, v156
	v_add_f32_e32 v154, v154, v155
	v_cvt_pk_bf16_f32 v96, v96, v97
	v_cvt_pk_bf16_f32 v97, v98, v99
	v_cvt_pk_bf16_f32 v100, v100, v101
	v_cvt_pk_bf16_f32 v101, v102, v103
	s_waitcnt lgkmcnt(0)
	s_add_i32 s93, s79, 0xffffffc0
	s_mov_b32 m0, s16
	v_add_u32_e32 v164, s93, v162
	v_med3_i32 v164, v164, 0, s41
	v_lshl_or_b32 v164, v164, 7, v220
	global_load_lds_dwordx4 v164, s[34:35]
	s_add_i32 m0, s16, 0x400
	v_add_u32_e32 v165, s93, v163
	v_med3_i32 v165, v165, 0, s41
	v_lshl_or_b32 v165, v165, 7, v221
	global_load_lds_dwordx4 v165, s[34:35]
	s_waitcnt vmcnt(8)
	v_add_u32_e32 v72, s12, v225
	v_add_u32_e32 v73, s12, v226
	v_add_u32_e32 v74, s12, v227
	v_add_u32_e32 v75, s12, v228
	ds_read_b64_tr_b16 v[88:89], v72
	ds_read_b64_tr_b16 v[90:91], v73
	ds_read_b64_tr_b16 v[92:93], v74
	ds_read_b64_tr_b16 v[94:95], v75
	v_mfma_f32_16x16x16_bf16 v[112:115], v[202:203], v[60:61], v[112:115]
	v_mfma_f32_16x16x16_bf16 v[116:119], v[204:205], v[60:61], v[116:119]
	v_mfma_f32_16x16x16_bf16 v[120:123], v[206:207], v[60:61], v[120:123]
	v_mfma_f32_16x16x16_bf16 v[124:127], v[208:209], v[60:61], v[124:127]
	v_cvt_pk_bf16_f32 v104, v104, v105
	v_cvt_pk_bf16_f32 v105, v106, v107
	v_cvt_pk_bf16_f32 v108, v108, v109
	v_cvt_pk_bf16_f32 v109, v110, v111
	v_add_u32_e32 v157, s42, v188
	s_lshl_b32 s90, s43, 7
	v_lshlrev_b32_e32 v158, 11, v157
	v_add3_u32 v158, v158, s90, v233
	v_mov_b32_e32 v76, v96
	v_mov_b32_e32 v77, v97
	v_mov_b32_e32 v78, v100
	v_mov_b32_e32 v79, v101
	s_waitcnt lgkmcnt(0)
	s_add_i32 s93, s79, 0xffffffd0
	s_mov_b32 m0, s12
	v_add_u32_e32 v164, s93, v162
	v_med3_i32 v164, v164, 0, s41
	v_lshl_or_b32 v164, v164, 7, v220
	global_load_lds_dwordx4 v164, s[34:35]
	s_add_i32 m0, s12, 0x400
	v_add_u32_e32 v165, s93, v163
	v_med3_i32 v165, v165, 0, s41
	v_lshl_or_b32 v165, v165, 7, v221
	global_load_lds_dwordx4 v165, s[34:35]
	s_waitcnt vmcnt(8)
	v_add_u32_e32 v72, s13, v225
	v_add_u32_e32 v73, s13, v226
	v_add_u32_e32 v74, s13, v227
	v_add_u32_e32 v75, s13, v228
	ds_read_b64_tr_b16 v[202:203], v72
	ds_read_b64_tr_b16 v[204:205], v73
	ds_read_b64_tr_b16 v[206:207], v74
	ds_read_b64_tr_b16 v[208:209], v75
	v_mfma_f32_16x16x16_bf16 v[112:115], v[88:89], v[64:65], v[112:115]
	v_mfma_f32_16x16x16_bf16 v[116:119], v[90:91], v[64:65], v[116:119]
	v_mfma_f32_16x16x16_bf16 v[120:123], v[92:93], v[64:65], v[120:123]
	v_mfma_f32_16x16x16_bf16 v[124:127], v[94:95], v[64:65], v[124:127]
	s_nop 1
	v_permlane16_swap_b32_e32 v76, v78
	v_permlane16_swap_b32_e32 v77, v79
	v_mov_b32_e32 v80, v104
	v_mov_b32_e32 v81, v105
	v_mov_b32_e32 v82, v108
	v_mov_b32_e32 v83, v109
	s_nop 1
	v_permlane16_swap_b32_e32 v80, v82
	v_permlane16_swap_b32_e32 v81, v83
	v_mov_b32_e32 v155, v154
	s_nop 1
	v_permlane16_swap_b32_e32 v154, v155
	s_waitcnt lgkmcnt(0)
	s_add_i32 s93, s79, 0xffffffe0
	s_mov_b32 m0, s13
	v_add_u32_e32 v164, s93, v162
	v_med3_i32 v164, v164, 0, s41
	v_lshl_or_b32 v164, v164, 7, v220
	global_load_lds_dwordx4 v164, s[34:35]
	s_add_i32 m0, s13, 0x400
	v_add_u32_e32 v165, s93, v163
	v_med3_i32 v165, v165, 0, s41
	v_lshl_or_b32 v165, v165, 7, v221
	global_load_lds_dwordx4 v165, s[34:35]
	v_mfma_f32_16x16x16_bf16 v[112:115], v[202:203], v[68:69], v[112:115]
	v_mfma_f32_16x16x16_bf16 v[116:119], v[204:205], v[68:69], v[116:119]
	v_mfma_f32_16x16x16_bf16 v[120:123], v[206:207], v[68:69], v[120:123]
	v_mfma_f32_16x16x16_bf16 v[124:127], v[208:209], v[68:69], v[124:127]
	v_add_f32_e32 v154, v154, v155
	v_mov_b32_e32 v155, v154
	s_nop 1
	v_permlane32_swap_b32_e32 v154, v155
	v_add_f32_e32 v154, v154, v155
	v_mul_u32_u24_e32 v157, 48, v157
	s_lshl_b32 s90, s43, 2
	v_add_u32_e32 v157, s90, v157
	s_nop 1
	global_store_dwordx4 v158, v[76:79], s[48:49] offset:0
	global_store_dwordx4 v158, v[80:83], s[48:49] offset:64
	s_and_saveexec_b64 s[80:81], s[74:75]
	global_store_dword v157, v154, s[50:51]
	s_mov_b64 exec, s[80:81]
	s_waitcnt lgkmcnt(0)
	v_max_f32_e32 v146, v182, v186
	v_sub_f32_e32 v148, v182, v146
	v_sub_f32_e32 v150, v186, v146
	v_exp_f32_e32 v148, v148
	v_exp_f32_e32 v150, v150
	v_mov_b32_e32 v186, v146
	v_mul_f32_e32 v187, v187, v150
	v_fmac_f32_e32 v187, v183, v148
	v_pk_mul_f32 v[112:113], v[150:151], v[112:113] op_sel_hi:[0,1]
	v_pk_mul_f32 v[114:115], v[150:151], v[114:115] op_sel_hi:[0,1]
	v_pk_mul_f32 v[116:117], v[150:151], v[116:117] op_sel_hi:[0,1]
	v_pk_mul_f32 v[118:119], v[150:151], v[118:119] op_sel_hi:[0,1]
	v_pk_mul_f32 v[120:121], v[150:151], v[120:121] op_sel_hi:[0,1]
	v_pk_mul_f32 v[122:123], v[150:151], v[122:123] op_sel_hi:[0,1]
	v_pk_mul_f32 v[124:125], v[150:151], v[124:125] op_sel_hi:[0,1]
	v_pk_mul_f32 v[126:127], v[150:151], v[126:127] op_sel_hi:[0,1]
	v_pk_fma_f32 v[112:113], v[148:149], v[166:167], v[112:113] op_sel_hi:[0,1,1]
	v_pk_fma_f32 v[114:115], v[148:149], v[168:169], v[114:115] op_sel_hi:[0,1,1]
	v_pk_fma_f32 v[116:117], v[148:149], v[170:171], v[116:117] op_sel_hi:[0,1,1]
	v_pk_fma_f32 v[118:119], v[148:149], v[172:173], v[118:119] op_sel_hi:[0,1,1]
	v_pk_fma_f32 v[120:121], v[148:149], v[174:175], v[120:121] op_sel_hi:[0,1,1]
	v_pk_fma_f32 v[122:123], v[148:149], v[176:177], v[122:123] op_sel_hi:[0,1,1]
	v_pk_fma_f32 v[124:125], v[148:149], v[178:179], v[124:125] op_sel_hi:[0,1,1]
	v_pk_fma_f32 v[126:127], v[148:149], v[180:181], v[126:127] op_sel_hi:[0,1,1]
	v_div_scale_f32 v147, s[94:95], v187, v187, 1.0
	v_rcp_f32_e32 v148, v147
	v_div_scale_f32 v149, vcc, 1.0, v187, 1.0
	v_fma_f32 v150, -v147, v148, 1.0
	v_fmac_f32_e32 v148, v150, v148
	v_mul_f32_e32 v150, v149, v148
	v_fma_f32 v151, -v147, v150, v149
	v_fmac_f32_e32 v150, v151, v148
	v_fma_f32 v147, -v147, v150, v149
	s_nop 1
	v_div_fmas_f32 v147, v147, v148, v150
	v_div_fixup_f32 v152, v147, v187, 1.0
	v_pk_mul_f32 v[112:113], v[152:153], v[112:113] op_sel_hi:[0,1]
	v_pk_mul_f32 v[114:115], v[152:153], v[114:115] op_sel_hi:[0,1]
	v_pk_mul_f32 v[116:117], v[152:153], v[116:117] op_sel_hi:[0,1]
	v_pk_mul_f32 v[118:119], v[152:153], v[118:119] op_sel_hi:[0,1]
	v_pk_mul_f32 v[120:121], v[152:153], v[120:121] op_sel_hi:[0,1]
	v_pk_mul_f32 v[122:123], v[152:153], v[122:123] op_sel_hi:[0,1]
	v_pk_mul_f32 v[124:125], v[152:153], v[124:125] op_sel_hi:[0,1]
	v_pk_mul_f32 v[126:127], v[152:153], v[126:127] op_sel_hi:[0,1]
	v_mul_f32_e32 v155, v113, v113
	v_mul_f32_e32 v156, v115, v115
	v_fmac_f32_e32 v155, v112, v112
	v_fmac_f32_e32 v156, v114, v114
	v_add_f32_e32 v154, v155, v156
	v_mul_f32_e32 v155, v117, v117
	v_mul_f32_e32 v156, v119, v119
	v_fmac_f32_e32 v155, v116, v116
	v_fmac_f32_e32 v156, v118, v118
	v_add_f32_e32 v155, v155, v156
	v_add_f32_e32 v154, v154, v155
	v_mul_f32_e32 v155, v121, v121
	v_mul_f32_e32 v156, v123, v123
	v_fmac_f32_e32 v155, v120, v120
	v_fmac_f32_e32 v156, v122, v122
	v_add_f32_e32 v155, v155, v156
	v_add_f32_e32 v154, v154, v155
	v_mul_f32_e32 v155, v125, v125
	v_mul_f32_e32 v156, v127, v127
	v_fmac_f32_e32 v155, v124, v124
	v_fmac_f32_e32 v156, v126, v126
	v_add_f32_e32 v155, v155, v156
	v_add_f32_e32 v154, v154, v155
	v_cvt_pk_bf16_f32 v112, v112, v113
	v_cvt_pk_bf16_f32 v113, v114, v115
	v_cvt_pk_bf16_f32 v116, v116, v117
	v_cvt_pk_bf16_f32 v117, v118, v119
	v_cvt_pk_bf16_f32 v120, v120, v121
	v_cvt_pk_bf16_f32 v121, v122, v123
	v_cvt_pk_bf16_f32 v124, v124, v125
	v_cvt_pk_bf16_f32 v125, v126, v127
	v_add_u32_e32 v157, s42, v189
	s_lshl_b32 s90, s43, 7
	v_lshlrev_b32_e32 v158, 11, v157
	v_add3_u32 v158, v158, s90, v233
	v_mov_b32_e32 v160, v112
	v_mov_b32_e32 v161, v113
	v_mov_b32_e32 v162, v116
	v_mov_b32_e32 v163, v117
	s_nop 1
	v_permlane16_swap_b32_e32 v160, v162
	v_permlane16_swap_b32_e32 v161, v163
	s_nop 1
	global_store_dwordx4 v158, v[160:163], s[48:49] offset:0
	s_nop 1
	v_mov_b32_e32 v160, v120
	v_mov_b32_e32 v161, v121
	v_mov_b32_e32 v162, v124
	v_mov_b32_e32 v163, v125
	s_nop 1
	v_permlane16_swap_b32_e32 v160, v162
	v_permlane16_swap_b32_e32 v161, v163
	s_nop 1
	global_store_dwordx4 v158, v[160:163], s[48:49] offset:64
	s_nop 1
	v_mov_b32_e32 v155, v154
	s_nop 1
	v_permlane16_swap_b32_e32 v154, v155
	v_add_f32_e32 v154, v154, v155
	v_mov_b32_e32 v155, v154
	s_nop 1
	v_permlane32_swap_b32_e32 v154, v155
	v_add_f32_e32 v154, v154, v155
	v_mul_u32_u24_e32 v157, 48, v157
	s_lshl_b32 s90, s43, 2
	v_add_u32_e32 v157, s90, v157
	s_and_saveexec_b64 s[80:81], s[74:75]
	global_store_dword v157, v154, s[50:51]
	s_mov_b64 exec, s[80:81]
	s_waitcnt lgkmcnt(0)
	s_barrier
	s_mov_b32 s90, s14
	s_mov_b32 s91, s15
	s_mov_b32 s92, s16
	s_mov_b32 s93, s12
	s_mov_b32 s97, s13
	s_mov_b32 s12, s90
	s_mov_b32 s13, s91
	s_mov_b32 s14, s92
	s_mov_b32 s15, s93
	s_mov_b32 s16, s97
	s_mov_b64 s[18:19], s[30:31]
	s_mov_b64 s[20:21], s[34:35]
	s_mov_b64 s[24:25], s[36:37]
	s_mov_b32 s38, s39
	s_mov_b32 s40, s41
	s_mov_b32 s42, s44
	s_mov_b32 s43, s45
	s_mov_b32 s9, 0
	s_add_i32 s11, s11, s66
	s_cmpk_lt_u32 s11, 0x900
	s_cbranch_scc1 .Latt_unit
	v_readlane_b32 s0, v244, 20
	s_bfe_u32 s3, s0, 0x20006
